# GEMM epilogues (upq, upk, merge_a, merge_b): hoisted/batched ssq, gate and partial loads with counted waits
# baseline (speedup 1.0000x reference)
; __device__ __forceinline__ void st8(bf16_t* p, f32x4 a, f32x4 b) { u32x4 w; w.x = pk2(a[0], a[1]); w.y = pk2(a[2], a[3]); w.z = pk2(b[0], b[1]); w.w = pk2(b[2], b[3]); *(u32x4*)p = w; }
;     __device__ __forceinline__ void operator()(ACC_T, const pg8::Unit& u, int wr, int wc, int fr, int fq) const {
;         const int pn = u.pn, row0 = u.pm * 256 + wr * 64 + fr, cw = wc * 32 + 8 * fq;
; #pragma unroll
;         for (int ai = 0; ai < 2; ++ai)
; #pragma unroll
;             for (int m = 0; m < 4; ++m) { const int row = row0 + ai * 128 + m * 16; const float* sp = ssq + tbase + row; const float rs = rsqrtf(((sp[0] + sp[TT]) + (sp[2 * TT] + sp[3 * TT])) * (1.f / 256.f) + EPS) * c2;
; #pragma unroll
;                 for (int bj = 0; bj < 2; ++bj) { const f32x4 v0 = acc[ai][bj][m][0] * rs, v1 = acc[ai][bj][m][1] * rs;
;                     if (pn < 4) st8(QN + (unsigned)row * 1024u + pn * 256 + cw + bj * 128, v0, v1);
;                     else { const int colr = (pn - 4) * 256 + cw + bj * 128, g8 = (colr & 63) >> 3;
;                         const f32x4* rp = (const f32x4*)(rope + (unsigned)((tbase + row) * 64 + 8 * g8)); const f32x4 c01 = rp[0], c23 = rp[1];
;                         f32x4 o1, o2;
;                         o1[0] = v0[0] * c01[0] - v1[0] * c01[1]; o2[0] = v0[0] * c01[1] + v1[0] * c01[0];
;                         o1[1] = v0[1] * c01[2] - v1[1] * c01[3]; o2[1] = v0[1] * c01[3] + v1[1] * c01[2];
;                         o1[2] = v0[2] * c23[0] - v1[2] * c23[1]; o2[2] = v0[2] * c23[1] + v1[2] * c23[0];
;                         o1[3] = v0[3] * c23[2] - v1[3] * c23[3]; o2[3] = v0[3] * c23[3] + v1[3] * c23[2];
;                         st8(QR + (unsigned)row * 512u + colr, o1, o2); } }
;                 asm volatile("" ::: "memory"); }
;     }
.LBB0_606:
	s_lshl_b32 s2, s90, 8
	v_mov_b32_e32 v0, v154
	v_mov_b32_e32 v138, v155
	s_add_i32 s2, s2, s68
	s_mov_b32 s97, 0x40000
	v_add_u32_e32 v144, s2, v0
	v_ashrrev_i32_e32 v145, 31, v144
	v_lshl_add_u64 v[142:143], v[144:145], 2, s[80:81]
	s_cmp_gt_i32 s40, 3
	v_add_co_u32_e32 v148, vcc, s97, v142
	s_cselect_b64 s[92:93], -1, 0
	s_lshl_b32 s90, s40, 8
	v_addc_co_u32_e32 v149, vcc, 0, v143, vcc
	s_mov_b32 s96, 0x80000
	v_lshl_add_u32 v138, v138, 3, s71
	s_add_i32 s2, s90, 0xfffffc00
	v_add_co_u32_e32 v150, vcc, s96, v142
	v_add_u32_e32 v140, s2, v138
	s_nop 0
	v_addc_co_u32_e32 v151, vcc, 0, v143, vcc
	s_mov_b32 s2, 0xc0000
	global_load_dword v146, v[142:143], off
	global_load_dword v147, v[150:151], off
	v_add_co_u32_e32 v150, vcc, s2, v142
	global_load_dword v148, v[148:149], off
	s_nop 0
	v_addc_co_u32_e32 v151, vcc, 0, v143, vcc
	global_load_dword v149, v[150:151], off
	v_and_b32_e32 v158, 56, v138
	v_ashrrev_i32_e32 v141, 31, v140
	v_add_co_u32_e32 v200, vcc, 0x40000, v142
	s_nop 1
	v_addc_co_u32_e32 v201, vcc, 0, v143, vcc
	v_add_co_u32_e32 v202, vcc, 0x80000, v142
	s_nop 1
	v_addc_co_u32_e32 v203, vcc, 0, v143, vcc
	v_add_co_u32_e32 v204, vcc, 0xc0000, v142
	s_nop 1
	v_addc_co_u32_e32 v205, vcc, 0, v143, vcc
	global_load_dword v172, v[142:143], off offset:64
	global_load_dword v174, v[200:201], off offset:64
	global_load_dword v173, v[202:203], off offset:64
	global_load_dword v175, v[204:205], off offset:64
	global_load_dword v176, v[142:143], off offset:128
	global_load_dword v178, v[200:201], off offset:128
	global_load_dword v177, v[202:203], off offset:128
	global_load_dword v179, v[204:205], off offset:128
	global_load_dword v180, v[142:143], off offset:192
	global_load_dword v182, v[200:201], off offset:192
	global_load_dword v181, v[202:203], off offset:192
	global_load_dword v183, v[204:205], off offset:192
	global_load_dword v184, v[142:143], off offset:512
	global_load_dword v186, v[200:201], off offset:512
	global_load_dword v185, v[202:203], off offset:512
	global_load_dword v187, v[204:205], off offset:512
	global_load_dword v188, v[142:143], off offset:576
	global_load_dword v190, v[200:201], off offset:576
	global_load_dword v189, v[202:203], off offset:576
	global_load_dword v191, v[204:205], off offset:576
	global_load_dword v192, v[142:143], off offset:640
	global_load_dword v194, v[200:201], off offset:640
	global_load_dword v193, v[202:203], off offset:640
	global_load_dword v195, v[204:205], off offset:640
	global_load_dword v196, v[142:143], off offset:704
	global_load_dword v198, v[200:201], off offset:704
	global_load_dword v197, v[202:203], off offset:704
	global_load_dword v199, v[204:205], off offset:704
	s_waitcnt vmcnt(28)
	v_pk_add_f32 v[146:147], v[146:147], v[148:149]
	s_nop 0
	v_add_f32_e32 v0, v146, v147
	v_fmamk_f32 v0, v0, 0x3b800000, v220
	v_cmp_gt_f32_e32 vcc, s51, v0
	v_mul_f32_e32 v139, 0x4b800000, v0
	s_nop 0
	v_cndmask_b32_e32 v0, v0, v139, vcc
	v_rsq_f32_e32 v0, v0
	s_nop 0
	v_mul_f32_e32 v139, 0x45800000, v0
	v_cndmask_b32_e32 v0, v0, v139, vcc
	v_mul_f32_e32 v146, 0x3dd53b94, v0
	v_lshlrev_b32_e32 v0, 9, v144
	v_add_u32_e32 v139, s78, v144
	v_pk_mul_f32 v[128:129], v[128:129], v[146:147] op_sel_hi:[1,0]
	v_pk_mul_f32 v[126:127], v[126:127], v[146:147] op_sel_hi:[1,0]
	v_pk_mul_f32 v[124:125], v[124:125], v[146:147] op_sel_hi:[1,0]
	v_pk_mul_f32 v[122:123], v[122:123], v[146:147] op_sel_hi:[1,0]
	s_and_b64 vcc, exec, s[92:93]
	v_lshl_or_b32 v150, v139, 6, v158
	v_lshl_add_u64 v[148:149], v[0:1], 1, s[42:43]
	s_cbranch_vccz .LBB0_608
	v_mov_b32_e32 v151, v1
	v_lshl_add_u64 v[152:153], v[150:151], 2, s[64:65]
	global_load_dwordx4 v[160:163], v[152:153], off offset:16
	global_load_dwordx4 v[164:167], v[152:153], off
	v_lshl_add_u64 v[170:171], v[140:141], 1, v[148:149]
	s_mov_b64 s[8:9], 0
	s_waitcnt vmcnt(0)
	v_mov_b32_e32 v153, v166
	v_mov_b32_e32 v166, v165
	v_mov_b32_e32 v152, v164
	v_pk_mul_f32 v[164:165], v[122:123], v[166:167]
	s_nop 0
	v_pk_fma_f32 v[164:165], v[126:127], v[152:153], v[164:165] neg_lo:[0,0,1] neg_hi:[0,0,1]
	v_pk_mul_f32 v[152:153], v[122:123], v[152:153]
	s_nop 0
	v_pk_fma_f32 v[152:153], v[126:127], v[166:167], v[152:153]
	v_mov_b32_e32 v167, v162
	v_mov_b32_e32 v162, v161
	v_mov_b32_e32 v166, v160
	v_pk_mul_f32 v[160:161], v[124:125], v[162:163]
	s_nop 0
	v_pk_fma_f32 v[168:169], v[128:129], v[166:167], v[160:161] neg_lo:[0,0,1] neg_hi:[0,0,1]
	v_pk_mul_f32 v[160:161], v[124:125], v[166:167]
	s_nop 0
	v_pk_fma_f32 v[166:167], v[128:129], v[162:163], v[160:161]
	v_cvt_pk_bf16_f32 v160, v164, v165
	v_cvt_pk_bf16_f32 v161, v168, v169
	v_cvt_pk_bf16_f32 v162, v152, v153
	v_cvt_pk_bf16_f32 v163, v166, v167
	global_store_dwordx4 v[170:171], v[160:163], off sc1

; __device__ __forceinline__ void st8(bf16_t* p, f32x4 a, f32x4 b) { u32x4 w; w.x = pk2(a[0], a[1]); w.y = pk2(a[2], a[3]); w.z = pk2(b[0], b[1]); w.w = pk2(b[2], b[3]); *(u32x4*)p = w; }
;     __device__ __forceinline__ void operator()(ACC_T, const pg8::Unit& u, int wr, int wc, int fr, int fq) const {
;         const int pn = u.pn, row0 = u.pm * 256 + wr * 64 + fr, cw = wc * 32 + 8 * fq;
; #pragma unroll
;         for (int ai = 0; ai < 2; ++ai)
; #pragma unroll
;             for (int m = 0; m < 4; ++m) { const int row = row0 + ai * 128 + m * 16; const float* sp = ssq + tbase + row; const float rs = rsqrtf(((sp[0] + sp[TT]) + (sp[2 * TT] + sp[3 * TT])) * (1.f / 256.f) + EPS) * c2;
; #pragma unroll
;                 for (int bj = 0; bj < 2; ++bj) { const f32x4 v0 = acc[ai][bj][m][0] * rs, v1 = acc[ai][bj][m][1] * rs;
;                     if (pn < 4) st8(QN + (unsigned)row * 1024u + pn * 256 + cw + bj * 128, v0, v1);
;                     else { const int colr = (pn - 4) * 256 + cw + bj * 128, g8 = (colr & 63) >> 3;
;                         const f32x4* rp = (const f32x4*)(rope + (unsigned)((tbase + row) * 64 + 8 * g8)); const f32x4 c01 = rp[0], c23 = rp[1];
;                         f32x4 o1, o2;
;                         o1[0] = v0[0] * c01[0] - v1[0] * c01[1]; o2[0] = v0[0] * c01[1] + v1[0] * c01[0];
;                         o1[1] = v0[1] * c01[2] - v1[1] * c01[3]; o2[1] = v0[1] * c01[3] + v1[1] * c01[2];
;                         o1[2] = v0[2] * c23[0] - v1[2] * c23[1]; o2[2] = v0[2] * c23[1] + v1[2] * c23[0];
;                         o1[3] = v0[3] * c23[2] - v1[3] * c23[3]; o2[3] = v0[3] * c23[3] + v1[3] * c23[2];
;                         st8(QR + (unsigned)row * 512u + colr, o1, o2); } }
;                 asm volatile("" ::: "memory"); }
;     }
.LBB0_614:
	s_nop 1
	v_add_co_u32_e32 v118, vcc, 0x40000, v142
	s_nop 0
	v_addc_co_u32_e32 v119, vcc, 0, v143, vcc
	v_add_co_u32_e32 v120, vcc, 0x80000, v142
	s_nop 0
	v_addc_co_u32_e32 v121, vcc, 0, v143, vcc
	v_add_co_u32_e32 v120, vcc, 0xc0000, v142
	v_add_u32_e32 v115, 16, v144
	s_nop 0
	v_addc_co_u32_e32 v121, vcc, 0, v143, vcc
	s_mov_b64 s[8:9], -1
	s_nop 1
	s_waitcnt vmcnt(26)
	v_pk_add_f32 v[116:117], v[172:173], v[174:175]
	s_nop 0
	v_add_f32_e32 v0, v116, v117
	v_fmamk_f32 v0, v0, 0x3b800000, v220
	v_cmp_gt_f32_e32 vcc, s51, v0
	v_mul_f32_e32 v114, 0x4b800000, v0
	v_add_u32_e32 v116, s78, v115
	v_cndmask_b32_e32 v0, v0, v114, vcc
	v_rsq_f32_e32 v0, v0
	v_lshl_or_b32 v118, v116, 6, v158
	v_mul_f32_e32 v114, 0x45800000, v0
	v_cndmask_b32_e32 v0, v0, v114, vcc
	v_mul_f32_e32 v114, 0x3dd53b94, v0
	v_lshlrev_b32_e32 v0, 9, v115
	v_pk_mul_f32 v[112:113], v[112:113], v[114:115] op_sel_hi:[1,0]
	v_pk_mul_f32 v[110:111], v[110:111], v[114:115] op_sel_hi:[1,0]
	v_pk_mul_f32 v[108:109], v[108:109], v[114:115] op_sel_hi:[1,0]
	v_pk_mul_f32 v[106:107], v[106:107], v[114:115] op_sel_hi:[1,0]
	s_and_b64 vcc, exec, s[40:41]
	v_lshl_add_u64 v[116:117], v[0:1], 1, s[42:43]
	s_cbranch_vccnz .LBB0_616
	v_mov_b32_e32 v119, v1
	v_lshl_add_u64 v[124:125], v[118:119], 2, s[64:65]
	global_load_dwordx4 v[120:123], v[124:125], off offset:16
	s_nop 0
	global_load_dwordx4 v[124:127], v[124:125], off
	v_lshl_add_u64 v[148:149], v[140:141], 1, v[116:117]
	s_mov_b64 s[8:9], 0
	s_waitcnt vmcnt(0)
	v_mov_b32_e32 v129, v126
	v_mov_b32_e32 v126, v125
	v_mov_b32_e32 v128, v124
	v_pk_mul_f32 v[124:125], v[106:107], v[126:127]
	s_nop 0
	v_pk_fma_f32 v[124:125], v[110:111], v[128:129], v[124:125] neg_lo:[0,0,1] neg_hi:[0,0,1]
	v_pk_mul_f32 v[128:129], v[106:107], v[128:129]
	s_nop 0
	v_pk_fma_f32 v[126:127], v[110:111], v[126:127], v[128:129]
	v_mov_b32_e32 v129, v122
	v_mov_b32_e32 v122, v121
	v_mov_b32_e32 v128, v120
	v_pk_mul_f32 v[120:121], v[108:109], v[122:123]
	s_nop 0
	v_pk_fma_f32 v[146:147], v[112:113], v[128:129], v[120:121] neg_lo:[0,0,1] neg_hi:[0,0,1]
	v_pk_mul_f32 v[120:121], v[108:109], v[128:129]
	s_nop 0
	v_pk_fma_f32 v[128:129], v[112:113], v[122:123], v[120:121]
	v_cvt_pk_bf16_f32 v120, v124, v125
	v_cvt_pk_bf16_f32 v121, v146, v147
	v_cvt_pk_bf16_f32 v122, v126, v127
	v_cvt_pk_bf16_f32 v123, v128, v129
	global_store_dwordx4 v[148:149], v[120:123], off sc1

; __device__ __forceinline__ void st8(bf16_t* p, f32x4 a, f32x4 b) { u32x4 w; w.x = pk2(a[0], a[1]); w.y = pk2(a[2], a[3]); w.z = pk2(b[0], b[1]); w.w = pk2(b[2], b[3]); *(u32x4*)p = w; }
;     __device__ __forceinline__ void operator()(ACC_T, const pg8::Unit& u, int wr, int wc, int fr, int fq) const {
;         const int pn = u.pn, row0 = u.pm * 256 + wr * 64 + fr, cw = wc * 32 + 8 * fq;
; #pragma unroll
;         for (int ai = 0; ai < 2; ++ai)
; #pragma unroll
;             for (int m = 0; m < 4; ++m) { const int row = row0 + ai * 128 + m * 16; const float* sp = ssq + tbase + row; const float rs = rsqrtf(((sp[0] + sp[TT]) + (sp[2 * TT] + sp[3 * TT])) * (1.f / 256.f) + EPS) * c2;
; #pragma unroll
;                 for (int bj = 0; bj < 2; ++bj) { const f32x4 v0 = acc[ai][bj][m][0] * rs, v1 = acc[ai][bj][m][1] * rs;
;                     if (pn < 4) st8(QN + (unsigned)row * 1024u + pn * 256 + cw + bj * 128, v0, v1);
;                     else { const int colr = (pn - 4) * 256 + cw + bj * 128, g8 = (colr & 63) >> 3;
;                         const f32x4* rp = (const f32x4*)(rope + (unsigned)((tbase + row) * 64 + 8 * g8)); const f32x4 c01 = rp[0], c23 = rp[1];
;                         f32x4 o1, o2;
;                         o1[0] = v0[0] * c01[0] - v1[0] * c01[1]; o2[0] = v0[0] * c01[1] + v1[0] * c01[0];
;                         o1[1] = v0[1] * c01[2] - v1[1] * c01[3]; o2[1] = v0[1] * c01[3] + v1[1] * c01[2];
;                         o1[2] = v0[2] * c23[0] - v1[2] * c23[1]; o2[2] = v0[2] * c23[1] + v1[2] * c23[0];
;                         o1[3] = v0[3] * c23[2] - v1[3] * c23[3]; o2[3] = v0[3] * c23[3] + v1[3] * c23[2];
;                         st8(QR + (unsigned)row * 512u + colr, o1, o2); } }
;                 asm volatile("" ::: "memory"); }
;     }
.LBB0_622:
	s_nop 1
	v_add_co_u32_e32 v102, vcc, 0x40000, v142
	s_nop 0
	v_addc_co_u32_e32 v103, vcc, 0, v143, vcc
	v_add_co_u32_e32 v104, vcc, 0x80000, v142
	s_nop 0
	v_addc_co_u32_e32 v105, vcc, 0, v143, vcc
	v_add_co_u32_e32 v104, vcc, 0xc0000, v142
	v_add_u32_e32 v99, 32, v144
	s_nop 0
	v_addc_co_u32_e32 v105, vcc, 0, v143, vcc
	s_mov_b64 s[8:9], -1
	s_nop 1
	s_waitcnt vmcnt(24)
	v_pk_add_f32 v[100:101], v[176:177], v[178:179]
	s_nop 0
	v_add_f32_e32 v0, v100, v101
	v_fmamk_f32 v0, v0, 0x3b800000, v220
	v_cmp_gt_f32_e32 vcc, s51, v0
	v_mul_f32_e32 v98, 0x4b800000, v0
	v_add_u32_e32 v100, s78, v99
	v_cndmask_b32_e32 v0, v0, v98, vcc
	v_rsq_f32_e32 v0, v0
	v_lshl_or_b32 v102, v100, 6, v158
	v_mul_f32_e32 v98, 0x45800000, v0
	v_cndmask_b32_e32 v0, v0, v98, vcc
	v_mul_f32_e32 v98, 0x3dd53b94, v0
	v_lshlrev_b32_e32 v0, 9, v99
	v_pk_mul_f32 v[96:97], v[96:97], v[98:99] op_sel_hi:[1,0]
	v_pk_mul_f32 v[94:95], v[94:95], v[98:99] op_sel_hi:[1,0]
	v_pk_mul_f32 v[92:93], v[92:93], v[98:99] op_sel_hi:[1,0]
	v_pk_mul_f32 v[90:91], v[90:91], v[98:99] op_sel_hi:[1,0]
	s_and_b64 vcc, exec, s[40:41]
	v_lshl_add_u64 v[100:101], v[0:1], 1, s[42:43]
	s_cbranch_vccnz .LBB0_624
	v_mov_b32_e32 v103, v1
	v_lshl_add_u64 v[108:109], v[102:103], 2, s[64:65]
	global_load_dwordx4 v[104:107], v[108:109], off offset:16
	s_nop 0
	global_load_dwordx4 v[108:111], v[108:109], off
	v_lshl_add_u64 v[116:117], v[140:141], 1, v[100:101]
	s_mov_b64 s[8:9], 0
	s_waitcnt vmcnt(0)
	v_mov_b32_e32 v113, v110
	v_mov_b32_e32 v110, v109
	v_mov_b32_e32 v112, v108
	v_pk_mul_f32 v[108:109], v[90:91], v[110:111]
	s_nop 0
	v_pk_fma_f32 v[108:109], v[94:95], v[112:113], v[108:109] neg_lo:[0,0,1] neg_hi:[0,0,1]
	v_pk_mul_f32 v[112:113], v[90:91], v[112:113]
	s_nop 0
	v_pk_fma_f32 v[110:111], v[94:95], v[110:111], v[112:113]
	v_mov_b32_e32 v113, v106
	v_mov_b32_e32 v106, v105
	v_mov_b32_e32 v112, v104
	v_pk_mul_f32 v[104:105], v[92:93], v[106:107]
	s_nop 0
	v_pk_fma_f32 v[114:115], v[96:97], v[112:113], v[104:105] neg_lo:[0,0,1] neg_hi:[0,0,1]
	v_pk_mul_f32 v[104:105], v[92:93], v[112:113]
	s_nop 0
	v_pk_fma_f32 v[112:113], v[96:97], v[106:107], v[104:105]
	v_cvt_pk_bf16_f32 v104, v108, v109
	v_cvt_pk_bf16_f32 v105, v114, v115
	v_cvt_pk_bf16_f32 v106, v110, v111
	v_cvt_pk_bf16_f32 v107, v112, v113
	global_store_dwordx4 v[116:117], v[104:107], off sc1

; __device__ __forceinline__ void st8(bf16_t* p, f32x4 a, f32x4 b) { u32x4 w; w.x = pk2(a[0], a[1]); w.y = pk2(a[2], a[3]); w.z = pk2(b[0], b[1]); w.w = pk2(b[2], b[3]); *(u32x4*)p = w; }
;     __device__ __forceinline__ void operator()(ACC_T, const pg8::Unit& u, int wr, int wc, int fr, int fq) const {
;         const int pn = u.pn, row0 = u.pm * 256 + wr * 64 + fr, cw = wc * 32 + 8 * fq;
; #pragma unroll
;         for (int ai = 0; ai < 2; ++ai)
; #pragma unroll
;             for (int m = 0; m < 4; ++m) { const int row = row0 + ai * 128 + m * 16; const float* sp = ssq + tbase + row; const float rs = rsqrtf(((sp[0] + sp[TT]) + (sp[2 * TT] + sp[3 * TT])) * (1.f / 256.f) + EPS) * c2;
; #pragma unroll
;                 for (int bj = 0; bj < 2; ++bj) { const f32x4 v0 = acc[ai][bj][m][0] * rs, v1 = acc[ai][bj][m][1] * rs;
;                     if (pn < 4) st8(QN + (unsigned)row * 1024u + pn * 256 + cw + bj * 128, v0, v1);
;                     else { const int colr = (pn - 4) * 256 + cw + bj * 128, g8 = (colr & 63) >> 3;
;                         const f32x4* rp = (const f32x4*)(rope + (unsigned)((tbase + row) * 64 + 8 * g8)); const f32x4 c01 = rp[0], c23 = rp[1];
;                         f32x4 o1, o2;
;                         o1[0] = v0[0] * c01[0] - v1[0] * c01[1]; o2[0] = v0[0] * c01[1] + v1[0] * c01[0];
;                         o1[1] = v0[1] * c01[2] - v1[1] * c01[3]; o2[1] = v0[1] * c01[3] + v1[1] * c01[2];
;                         o1[2] = v0[2] * c23[0] - v1[2] * c23[1]; o2[2] = v0[2] * c23[1] + v1[2] * c23[0];
;                         o1[3] = v0[3] * c23[2] - v1[3] * c23[3]; o2[3] = v0[3] * c23[3] + v1[3] * c23[2];
;                         st8(QR + (unsigned)row * 512u + colr, o1, o2); } }
;                 asm volatile("" ::: "memory"); }
;     }
.LBB0_630:
	s_nop 1
	v_add_co_u32_e32 v86, vcc, 0x40000, v142
	s_nop 0
	v_addc_co_u32_e32 v87, vcc, 0, v143, vcc
	v_add_co_u32_e32 v88, vcc, 0x80000, v142
	s_nop 0
	v_addc_co_u32_e32 v89, vcc, 0, v143, vcc
	v_add_co_u32_e32 v88, vcc, 0xc0000, v142
	v_add_u32_e32 v83, 48, v144
	s_nop 0
	v_addc_co_u32_e32 v89, vcc, 0, v143, vcc
	s_mov_b64 s[8:9], -1
	s_nop 1
	s_waitcnt vmcnt(22)
	v_pk_add_f32 v[84:85], v[180:181], v[182:183]
	s_nop 0
	v_add_f32_e32 v0, v84, v85
	v_fmamk_f32 v0, v0, 0x3b800000, v220
	v_cmp_gt_f32_e32 vcc, s51, v0
	v_mul_f32_e32 v82, 0x4b800000, v0
	v_add_u32_e32 v84, s78, v83
	v_cndmask_b32_e32 v0, v0, v82, vcc
	v_rsq_f32_e32 v0, v0
	v_lshl_or_b32 v86, v84, 6, v158
	v_mul_f32_e32 v82, 0x45800000, v0
	v_cndmask_b32_e32 v0, v0, v82, vcc
	v_mul_f32_e32 v82, 0x3dd53b94, v0
	v_lshlrev_b32_e32 v0, 9, v83
	v_pk_mul_f32 v[80:81], v[80:81], v[82:83] op_sel_hi:[1,0]
	v_pk_mul_f32 v[78:79], v[78:79], v[82:83] op_sel_hi:[1,0]
	v_pk_mul_f32 v[76:77], v[76:77], v[82:83] op_sel_hi:[1,0]
	v_pk_mul_f32 v[74:75], v[74:75], v[82:83] op_sel_hi:[1,0]
	s_and_b64 vcc, exec, s[40:41]
	v_lshl_add_u64 v[84:85], v[0:1], 1, s[42:43]
	s_cbranch_vccnz .LBB0_632
	v_mov_b32_e32 v87, v1
	v_lshl_add_u64 v[92:93], v[86:87], 2, s[64:65]
	global_load_dwordx4 v[88:91], v[92:93], off offset:16
	s_nop 0
	global_load_dwordx4 v[92:95], v[92:93], off
	v_lshl_add_u64 v[100:101], v[140:141], 1, v[84:85]
	s_mov_b64 s[8:9], 0
	s_waitcnt vmcnt(0)
	v_mov_b32_e32 v97, v94
	v_mov_b32_e32 v94, v93
	v_mov_b32_e32 v96, v92
	v_pk_mul_f32 v[92:93], v[74:75], v[94:95]
	s_nop 0
	v_pk_fma_f32 v[92:93], v[78:79], v[96:97], v[92:93] neg_lo:[0,0,1] neg_hi:[0,0,1]
	v_pk_mul_f32 v[96:97], v[74:75], v[96:97]
	s_nop 0
	v_pk_fma_f32 v[94:95], v[78:79], v[94:95], v[96:97]
	v_mov_b32_e32 v97, v90
	v_mov_b32_e32 v90, v89
	v_mov_b32_e32 v96, v88
	v_pk_mul_f32 v[88:89], v[76:77], v[90:91]
	s_nop 0
	v_pk_fma_f32 v[98:99], v[80:81], v[96:97], v[88:89] neg_lo:[0,0,1] neg_hi:[0,0,1]
	v_pk_mul_f32 v[88:89], v[76:77], v[96:97]
	s_nop 0
	v_pk_fma_f32 v[96:97], v[80:81], v[90:91], v[88:89]
	v_cvt_pk_bf16_f32 v88, v92, v93
	v_cvt_pk_bf16_f32 v89, v98, v99
	v_cvt_pk_bf16_f32 v90, v94, v95
	v_cvt_pk_bf16_f32 v91, v96, v97
	global_store_dwordx4 v[100:101], v[88:91], off sc1

; __device__ __forceinline__ void st8(bf16_t* p, f32x4 a, f32x4 b) { u32x4 w; w.x = pk2(a[0], a[1]); w.y = pk2(a[2], a[3]); w.z = pk2(b[0], b[1]); w.w = pk2(b[2], b[3]); *(u32x4*)p = w; }
;     __device__ __forceinline__ void operator()(ACC_T, const pg8::Unit& u, int wr, int wc, int fr, int fq) const {
;         const int pn = u.pn, row0 = u.pm * 256 + wr * 64 + fr, cw = wc * 32 + 8 * fq;
; #pragma unroll
;         for (int ai = 0; ai < 2; ++ai)
; #pragma unroll
;             for (int m = 0; m < 4; ++m) { const int row = row0 + ai * 128 + m * 16; const float* sp = ssq + tbase + row; const float rs = rsqrtf(((sp[0] + sp[TT]) + (sp[2 * TT] + sp[3 * TT])) * (1.f / 256.f) + EPS) * c2;
; #pragma unroll
;                 for (int bj = 0; bj < 2; ++bj) { const f32x4 v0 = acc[ai][bj][m][0] * rs, v1 = acc[ai][bj][m][1] * rs;
;                     if (pn < 4) st8(QN + (unsigned)row * 1024u + pn * 256 + cw + bj * 128, v0, v1);
;                     else { const int colr = (pn - 4) * 256 + cw + bj * 128, g8 = (colr & 63) >> 3;
;                         const f32x4* rp = (const f32x4*)(rope + (unsigned)((tbase + row) * 64 + 8 * g8)); const f32x4 c01 = rp[0], c23 = rp[1];
;                         f32x4 o1, o2;
;                         o1[0] = v0[0] * c01[0] - v1[0] * c01[1]; o2[0] = v0[0] * c01[1] + v1[0] * c01[0];
;                         o1[1] = v0[1] * c01[2] - v1[1] * c01[3]; o2[1] = v0[1] * c01[3] + v1[1] * c01[2];
;                         o1[2] = v0[2] * c23[0] - v1[2] * c23[1]; o2[2] = v0[2] * c23[1] + v1[2] * c23[0];
;                         o1[3] = v0[3] * c23[2] - v1[3] * c23[3]; o2[3] = v0[3] * c23[3] + v1[3] * c23[2];
;                         st8(QR + (unsigned)row * 512u + colr, o1, o2); } }
;                 asm volatile("" ::: "memory"); }
;     }
.LBB0_638:
	s_nop 1
	v_add_co_u32_e32 v70, vcc, 0x40000, v142
	s_nop 0
	v_addc_co_u32_e32 v71, vcc, 0, v143, vcc
	v_add_co_u32_e32 v72, vcc, 0x80000, v142
	s_nop 0
	v_addc_co_u32_e32 v73, vcc, 0, v143, vcc
	v_add_co_u32_e32 v72, vcc, 0xc0000, v142
	v_add_u32_e32 v67, 0x80, v144
	s_nop 0
	v_addc_co_u32_e32 v73, vcc, 0, v143, vcc
	s_mov_b64 s[8:9], -1
	s_nop 1
	s_waitcnt vmcnt(20)
	v_pk_add_f32 v[68:69], v[184:185], v[186:187]
	s_nop 0
	v_add_f32_e32 v0, v68, v69
	v_fmamk_f32 v0, v0, 0x3b800000, v220
	v_cmp_gt_f32_e32 vcc, s51, v0
	v_mul_f32_e32 v66, 0x4b800000, v0
	v_add_u32_e32 v68, s78, v67
	v_cndmask_b32_e32 v0, v0, v66, vcc
	v_rsq_f32_e32 v0, v0
	v_lshl_or_b32 v70, v68, 6, v158
	v_mul_f32_e32 v66, 0x45800000, v0
	v_cndmask_b32_e32 v0, v0, v66, vcc
	v_mul_f32_e32 v66, 0x3dd53b94, v0
	v_lshlrev_b32_e32 v0, 9, v67
	v_pk_mul_f32 v[64:65], v[64:65], v[66:67] op_sel_hi:[1,0]
	v_pk_mul_f32 v[62:63], v[62:63], v[66:67] op_sel_hi:[1,0]
	v_pk_mul_f32 v[60:61], v[60:61], v[66:67] op_sel_hi:[1,0]
	v_pk_mul_f32 v[58:59], v[58:59], v[66:67] op_sel_hi:[1,0]
	s_and_b64 vcc, exec, s[40:41]
	v_lshl_add_u64 v[68:69], v[0:1], 1, s[42:43]
	s_cbranch_vccnz .LBB0_640
	v_mov_b32_e32 v71, v1
	v_lshl_add_u64 v[76:77], v[70:71], 2, s[64:65]
	global_load_dwordx4 v[72:75], v[76:77], off offset:16
	s_nop 0
	global_load_dwordx4 v[76:79], v[76:77], off
	v_lshl_add_u64 v[84:85], v[140:141], 1, v[68:69]
	s_mov_b64 s[8:9], 0
	s_waitcnt vmcnt(0)
	v_mov_b32_e32 v81, v78
	v_mov_b32_e32 v78, v77
	v_mov_b32_e32 v80, v76
	v_pk_mul_f32 v[76:77], v[58:59], v[78:79]
	s_nop 0
	v_pk_fma_f32 v[76:77], v[62:63], v[80:81], v[76:77] neg_lo:[0,0,1] neg_hi:[0,0,1]
	v_pk_mul_f32 v[80:81], v[58:59], v[80:81]
	s_nop 0
	v_pk_fma_f32 v[78:79], v[62:63], v[78:79], v[80:81]
	v_mov_b32_e32 v81, v74
	v_mov_b32_e32 v74, v73
	v_mov_b32_e32 v80, v72
	v_pk_mul_f32 v[72:73], v[60:61], v[74:75]
	s_nop 0
	v_pk_fma_f32 v[82:83], v[64:65], v[80:81], v[72:73] neg_lo:[0,0,1] neg_hi:[0,0,1]
	v_pk_mul_f32 v[72:73], v[60:61], v[80:81]
	s_nop 0
	v_pk_fma_f32 v[80:81], v[64:65], v[74:75], v[72:73]
	v_cvt_pk_bf16_f32 v72, v76, v77
	v_cvt_pk_bf16_f32 v73, v82, v83
	v_cvt_pk_bf16_f32 v74, v78, v79
	v_cvt_pk_bf16_f32 v75, v80, v81
	global_store_dwordx4 v[84:85], v[72:75], off sc1

; __device__ __forceinline__ void st8(bf16_t* p, f32x4 a, f32x4 b) { u32x4 w; w.x = pk2(a[0], a[1]); w.y = pk2(a[2], a[3]); w.z = pk2(b[0], b[1]); w.w = pk2(b[2], b[3]); *(u32x4*)p = w; }
;     __device__ __forceinline__ void operator()(ACC_T, const pg8::Unit& u, int wr, int wc, int fr, int fq) const {
;         const int pn = u.pn, row0 = u.pm * 256 + wr * 64 + fr, cw = wc * 32 + 8 * fq;
; #pragma unroll
;         for (int ai = 0; ai < 2; ++ai)
; #pragma unroll
;             for (int m = 0; m < 4; ++m) { const int row = row0 + ai * 128 + m * 16; const float* sp = ssq + tbase + row; const float rs = rsqrtf(((sp[0] + sp[TT]) + (sp[2 * TT] + sp[3 * TT])) * (1.f / 256.f) + EPS) * c2;
; #pragma unroll
;                 for (int bj = 0; bj < 2; ++bj) { const f32x4 v0 = acc[ai][bj][m][0] * rs, v1 = acc[ai][bj][m][1] * rs;
;                     if (pn < 4) st8(QN + (unsigned)row * 1024u + pn * 256 + cw + bj * 128, v0, v1);
;                     else { const int colr = (pn - 4) * 256 + cw + bj * 128, g8 = (colr & 63) >> 3;
;                         const f32x4* rp = (const f32x4*)(rope + (unsigned)((tbase + row) * 64 + 8 * g8)); const f32x4 c01 = rp[0], c23 = rp[1];
;                         f32x4 o1, o2;
;                         o1[0] = v0[0] * c01[0] - v1[0] * c01[1]; o2[0] = v0[0] * c01[1] + v1[0] * c01[0];
;                         o1[1] = v0[1] * c01[2] - v1[1] * c01[3]; o2[1] = v0[1] * c01[3] + v1[1] * c01[2];
;                         o1[2] = v0[2] * c23[0] - v1[2] * c23[1]; o2[2] = v0[2] * c23[1] + v1[2] * c23[0];
;                         o1[3] = v0[3] * c23[2] - v1[3] * c23[3]; o2[3] = v0[3] * c23[3] + v1[3] * c23[2];
;                         st8(QR + (unsigned)row * 512u + colr, o1, o2); } }
;                 asm volatile("" ::: "memory"); }
;     }
.LBB0_646:
	s_nop 1
	v_add_co_u32_e32 v54, vcc, 0x40000, v142
	s_nop 0
	v_addc_co_u32_e32 v55, vcc, 0, v143, vcc
	v_add_co_u32_e32 v56, vcc, 0x80000, v142
	s_nop 0
	v_addc_co_u32_e32 v57, vcc, 0, v143, vcc
	v_add_co_u32_e32 v56, vcc, 0xc0000, v142
	v_add_u32_e32 v51, 0x90, v144
	s_nop 0
	v_addc_co_u32_e32 v57, vcc, 0, v143, vcc
	s_mov_b64 s[8:9], -1
	s_nop 1
	s_waitcnt vmcnt(18)
	v_pk_add_f32 v[52:53], v[188:189], v[190:191]
	s_nop 0
	v_add_f32_e32 v0, v52, v53
	v_fmamk_f32 v0, v0, 0x3b800000, v220
	v_cmp_gt_f32_e32 vcc, s51, v0
	v_mul_f32_e32 v50, 0x4b800000, v0
	v_add_u32_e32 v52, s78, v51
	v_cndmask_b32_e32 v0, v0, v50, vcc
	v_rsq_f32_e32 v0, v0
	v_lshl_or_b32 v54, v52, 6, v158
	v_mul_f32_e32 v50, 0x45800000, v0
	v_cndmask_b32_e32 v0, v0, v50, vcc
	v_mul_f32_e32 v50, 0x3dd53b94, v0
	v_lshlrev_b32_e32 v0, 9, v51
	v_pk_mul_f32 v[48:49], v[48:49], v[50:51] op_sel_hi:[1,0]
	v_pk_mul_f32 v[46:47], v[46:47], v[50:51] op_sel_hi:[1,0]
	v_pk_mul_f32 v[44:45], v[44:45], v[50:51] op_sel_hi:[1,0]
	v_pk_mul_f32 v[42:43], v[42:43], v[50:51] op_sel_hi:[1,0]
	s_and_b64 vcc, exec, s[40:41]
	v_lshl_add_u64 v[52:53], v[0:1], 1, s[42:43]
	s_cbranch_vccnz .LBB0_648
	v_mov_b32_e32 v55, v1
	v_lshl_add_u64 v[60:61], v[54:55], 2, s[64:65]
	global_load_dwordx4 v[56:59], v[60:61], off offset:16
	s_nop 0
	global_load_dwordx4 v[60:63], v[60:61], off
	v_lshl_add_u64 v[68:69], v[140:141], 1, v[52:53]
	s_mov_b64 s[8:9], 0
	s_waitcnt vmcnt(0)
	v_mov_b32_e32 v65, v62
	v_mov_b32_e32 v62, v61
	v_mov_b32_e32 v64, v60
	v_pk_mul_f32 v[60:61], v[42:43], v[62:63]
	s_nop 0
	v_pk_fma_f32 v[60:61], v[46:47], v[64:65], v[60:61] neg_lo:[0,0,1] neg_hi:[0,0,1]
	v_pk_mul_f32 v[64:65], v[42:43], v[64:65]
	s_nop 0
	v_pk_fma_f32 v[62:63], v[46:47], v[62:63], v[64:65]
	v_mov_b32_e32 v65, v58
	v_mov_b32_e32 v58, v57
	v_mov_b32_e32 v64, v56
	v_pk_mul_f32 v[56:57], v[44:45], v[58:59]
	s_nop 0
	v_pk_fma_f32 v[66:67], v[48:49], v[64:65], v[56:57] neg_lo:[0,0,1] neg_hi:[0,0,1]
	v_pk_mul_f32 v[56:57], v[44:45], v[64:65]
	s_nop 0
	v_pk_fma_f32 v[64:65], v[48:49], v[58:59], v[56:57]
	v_cvt_pk_bf16_f32 v56, v60, v61
	v_cvt_pk_bf16_f32 v57, v66, v67
	v_cvt_pk_bf16_f32 v58, v62, v63
	v_cvt_pk_bf16_f32 v59, v64, v65
	global_store_dwordx4 v[68:69], v[56:59], off sc1

; __device__ __forceinline__ void st8(bf16_t* p, f32x4 a, f32x4 b) { u32x4 w; w.x = pk2(a[0], a[1]); w.y = pk2(a[2], a[3]); w.z = pk2(b[0], b[1]); w.w = pk2(b[2], b[3]); *(u32x4*)p = w; }
;     __device__ __forceinline__ void operator()(ACC_T, const pg8::Unit& u, int wr, int wc, int fr, int fq) const {
;         const int pn = u.pn, row0 = u.pm * 256 + wr * 64 + fr, cw = wc * 32 + 8 * fq;
; #pragma unroll
;         for (int ai = 0; ai < 2; ++ai)
; #pragma unroll
;             for (int m = 0; m < 4; ++m) { const int row = row0 + ai * 128 + m * 16; const float* sp = ssq + tbase + row; const float rs = rsqrtf(((sp[0] + sp[TT]) + (sp[2 * TT] + sp[3 * TT])) * (1.f / 256.f) + EPS) * c2;
; #pragma unroll
;                 for (int bj = 0; bj < 2; ++bj) { const f32x4 v0 = acc[ai][bj][m][0] * rs, v1 = acc[ai][bj][m][1] * rs;
;                     if (pn < 4) st8(QN + (unsigned)row * 1024u + pn * 256 + cw + bj * 128, v0, v1);
;                     else { const int colr = (pn - 4) * 256 + cw + bj * 128, g8 = (colr & 63) >> 3;
;                         const f32x4* rp = (const f32x4*)(rope + (unsigned)((tbase + row) * 64 + 8 * g8)); const f32x4 c01 = rp[0], c23 = rp[1];
;                         f32x4 o1, o2;
;                         o1[0] = v0[0] * c01[0] - v1[0] * c01[1]; o2[0] = v0[0] * c01[1] + v1[0] * c01[0];
;                         o1[1] = v0[1] * c01[2] - v1[1] * c01[3]; o2[1] = v0[1] * c01[3] + v1[1] * c01[2];
;                         o1[2] = v0[2] * c23[0] - v1[2] * c23[1]; o2[2] = v0[2] * c23[1] + v1[2] * c23[0];
;                         o1[3] = v0[3] * c23[2] - v1[3] * c23[3]; o2[3] = v0[3] * c23[3] + v1[3] * c23[2];
;                         st8(QR + (unsigned)row * 512u + colr, o1, o2); } }
;                 asm volatile("" ::: "memory"); }
;     }
.LBB0_654:
	s_nop 1
	v_add_co_u32_e32 v38, vcc, 0x40000, v142
	s_nop 0
	v_addc_co_u32_e32 v39, vcc, 0, v143, vcc
	v_add_co_u32_e32 v40, vcc, 0x80000, v142
	s_nop 0
	v_addc_co_u32_e32 v41, vcc, 0, v143, vcc
	v_add_co_u32_e32 v40, vcc, 0xc0000, v142
	v_add_u32_e32 v35, 0xa0, v144
	s_nop 0
	v_addc_co_u32_e32 v41, vcc, 0, v143, vcc
	s_mov_b64 s[8:9], -1
	s_nop 1
	s_waitcnt vmcnt(16)
	v_pk_add_f32 v[36:37], v[192:193], v[194:195]
	s_nop 0
	v_add_f32_e32 v0, v36, v37
	v_fmamk_f32 v0, v0, 0x3b800000, v220
	v_cmp_gt_f32_e32 vcc, s51, v0
	v_mul_f32_e32 v34, 0x4b800000, v0
	v_add_u32_e32 v36, s78, v35
	v_cndmask_b32_e32 v0, v0, v34, vcc
	v_rsq_f32_e32 v0, v0
	v_lshl_or_b32 v38, v36, 6, v158
	v_mul_f32_e32 v34, 0x45800000, v0
	v_cndmask_b32_e32 v0, v0, v34, vcc
	v_mul_f32_e32 v34, 0x3dd53b94, v0
	v_lshlrev_b32_e32 v0, 9, v35
	v_pk_mul_f32 v[32:33], v[32:33], v[34:35] op_sel_hi:[1,0]
	v_pk_mul_f32 v[30:31], v[30:31], v[34:35] op_sel_hi:[1,0]
	v_pk_mul_f32 v[28:29], v[28:29], v[34:35] op_sel_hi:[1,0]
	v_pk_mul_f32 v[26:27], v[26:27], v[34:35] op_sel_hi:[1,0]
	s_and_b64 vcc, exec, s[40:41]
	v_lshl_add_u64 v[36:37], v[0:1], 1, s[42:43]
	s_cbranch_vccnz .LBB0_656
	v_mov_b32_e32 v39, v1
	v_lshl_add_u64 v[44:45], v[38:39], 2, s[64:65]
	global_load_dwordx4 v[40:43], v[44:45], off offset:16
	s_nop 0
	global_load_dwordx4 v[44:47], v[44:45], off
	v_lshl_add_u64 v[52:53], v[140:141], 1, v[36:37]
	s_mov_b64 s[8:9], 0
	s_waitcnt vmcnt(0)
	v_mov_b32_e32 v49, v46
	v_mov_b32_e32 v46, v45
	v_mov_b32_e32 v48, v44
	v_pk_mul_f32 v[44:45], v[26:27], v[46:47]
	s_nop 0
	v_pk_fma_f32 v[44:45], v[30:31], v[48:49], v[44:45] neg_lo:[0,0,1] neg_hi:[0,0,1]
	v_pk_mul_f32 v[48:49], v[26:27], v[48:49]
	s_nop 0
	v_pk_fma_f32 v[46:47], v[30:31], v[46:47], v[48:49]
	v_mov_b32_e32 v49, v42
	v_mov_b32_e32 v42, v41
	v_mov_b32_e32 v48, v40
	v_pk_mul_f32 v[40:41], v[28:29], v[42:43]
	s_nop 0
	v_pk_fma_f32 v[50:51], v[32:33], v[48:49], v[40:41] neg_lo:[0,0,1] neg_hi:[0,0,1]
	v_pk_mul_f32 v[40:41], v[28:29], v[48:49]
	s_nop 0
	v_pk_fma_f32 v[48:49], v[32:33], v[42:43], v[40:41]
	v_cvt_pk_bf16_f32 v40, v44, v45
	v_cvt_pk_bf16_f32 v41, v50, v51
	v_cvt_pk_bf16_f32 v42, v46, v47
	v_cvt_pk_bf16_f32 v43, v48, v49
	global_store_dwordx4 v[52:53], v[40:43], off sc1

; __device__ __forceinline__ void st8(bf16_t* p, f32x4 a, f32x4 b) { u32x4 w; w.x = pk2(a[0], a[1]); w.y = pk2(a[2], a[3]); w.z = pk2(b[0], b[1]); w.w = pk2(b[2], b[3]); *(u32x4*)p = w; }
;     __device__ __forceinline__ void operator()(ACC_T, const pg8::Unit& u, int wr, int wc, int fr, int fq) const {
;         const int pn = u.pn, row0 = u.pm * 256 + wr * 64 + fr, cw = wc * 32 + 8 * fq;
; #pragma unroll
;         for (int ai = 0; ai < 2; ++ai)
; #pragma unroll
;             for (int m = 0; m < 4; ++m) { const int row = row0 + ai * 128 + m * 16; const float* sp = ssq + tbase + row; const float rs = rsqrtf(((sp[0] + sp[TT]) + (sp[2 * TT] + sp[3 * TT])) * (1.f / 256.f) + EPS) * c2;
; #pragma unroll
;                 for (int bj = 0; bj < 2; ++bj) { const f32x4 v0 = acc[ai][bj][m][0] * rs, v1 = acc[ai][bj][m][1] * rs;
;                     if (pn < 4) st8(QN + (unsigned)row * 1024u + pn * 256 + cw + bj * 128, v0, v1);
;                     else { const int colr = (pn - 4) * 256 + cw + bj * 128, g8 = (colr & 63) >> 3;
;                         const f32x4* rp = (const f32x4*)(rope + (unsigned)((tbase + row) * 64 + 8 * g8)); const f32x4 c01 = rp[0], c23 = rp[1];
;                         f32x4 o1, o2;
;                         o1[0] = v0[0] * c01[0] - v1[0] * c01[1]; o2[0] = v0[0] * c01[1] + v1[0] * c01[0];
;                         o1[1] = v0[1] * c01[2] - v1[1] * c01[3]; o2[1] = v0[1] * c01[3] + v1[1] * c01[2];
;                         o1[2] = v0[2] * c23[0] - v1[2] * c23[1]; o2[2] = v0[2] * c23[1] + v1[2] * c23[0];
;                         o1[3] = v0[3] * c23[2] - v1[3] * c23[3]; o2[3] = v0[3] * c23[3] + v1[3] * c23[2];
;                         st8(QR + (unsigned)row * 512u + colr, o1, o2); } }
;                 asm volatile("" ::: "memory"); }
;     }
.LBB0_662:
	s_nop 1
	v_add_co_u32_e32 v22, vcc, 0x40000, v142
	s_nop 0
	v_addc_co_u32_e32 v23, vcc, 0, v143, vcc
	v_add_co_u32_e32 v24, vcc, 0x80000, v142
	s_nop 0
	v_addc_co_u32_e32 v25, vcc, 0, v143, vcc
	v_add_co_u32_e32 v24, vcc, 0xc0000, v142
	v_add_u32_e32 v19, 0xb0, v144
	s_nop 0
	v_addc_co_u32_e32 v25, vcc, 0, v143, vcc
	s_mov_b64 s[8:9], -1
	s_nop 1
	s_waitcnt vmcnt(14)
	v_pk_add_f32 v[20:21], v[196:197], v[198:199]
	s_nop 0
	v_add_f32_e32 v0, v20, v21
	v_fmamk_f32 v0, v0, 0x3b800000, v220
	v_cmp_gt_f32_e32 vcc, s51, v0
	v_mul_f32_e32 v18, 0x4b800000, v0
	v_add_u32_e32 v20, s78, v19
	v_cndmask_b32_e32 v0, v0, v18, vcc
	v_rsq_f32_e32 v0, v0
	v_lshl_or_b32 v22, v20, 6, v158
	v_mul_f32_e32 v18, 0x45800000, v0
	v_cndmask_b32_e32 v0, v0, v18, vcc
	v_mul_f32_e32 v18, 0x3dd53b94, v0
	v_lshlrev_b32_e32 v0, 9, v19
	v_pk_mul_f32 v[16:17], v[16:17], v[18:19] op_sel_hi:[1,0]
	v_pk_mul_f32 v[14:15], v[14:15], v[18:19] op_sel_hi:[1,0]
	v_pk_mul_f32 v[12:13], v[12:13], v[18:19] op_sel_hi:[1,0]
	v_pk_mul_f32 v[10:11], v[10:11], v[18:19] op_sel_hi:[1,0]
	s_and_b64 vcc, exec, s[40:41]
	v_lshl_add_u64 v[20:21], v[0:1], 1, s[42:43]
	s_cbranch_vccnz .LBB0_664
	v_mov_b32_e32 v23, v1
	v_lshl_add_u64 v[28:29], v[22:23], 2, s[64:65]
	global_load_dwordx4 v[24:27], v[28:29], off offset:16
	s_nop 0
	global_load_dwordx4 v[28:31], v[28:29], off
	v_lshl_add_u64 v[36:37], v[140:141], 1, v[20:21]
	s_mov_b64 s[8:9], 0
	s_waitcnt vmcnt(0)
	v_mov_b32_e32 v33, v30
	v_mov_b32_e32 v30, v29
	v_mov_b32_e32 v32, v28
	v_pk_mul_f32 v[28:29], v[10:11], v[30:31]
	s_nop 0
	v_pk_fma_f32 v[28:29], v[14:15], v[32:33], v[28:29] neg_lo:[0,0,1] neg_hi:[0,0,1]
	v_pk_mul_f32 v[32:33], v[10:11], v[32:33]
	s_nop 0
	v_pk_fma_f32 v[30:31], v[14:15], v[30:31], v[32:33]
	v_mov_b32_e32 v33, v26
	v_mov_b32_e32 v26, v25
	v_mov_b32_e32 v32, v24
	v_pk_mul_f32 v[24:25], v[12:13], v[26:27]
	s_nop 0
	v_pk_fma_f32 v[34:35], v[16:17], v[32:33], v[24:25] neg_lo:[0,0,1] neg_hi:[0,0,1]
	v_pk_mul_f32 v[24:25], v[12:13], v[32:33]
	s_nop 0
	v_pk_fma_f32 v[32:33], v[16:17], v[26:27], v[24:25]
	v_cvt_pk_bf16_f32 v24, v28, v29
	v_cvt_pk_bf16_f32 v25, v34, v35
	v_cvt_pk_bf16_f32 v26, v30, v31
	v_cvt_pk_bf16_f32 v27, v32, v33
	global_store_dwordx4 v[36:37], v[24:27], off sc1

; __device__ __forceinline__ void st8(bf16_t* p, f32x4 a, f32x4 b) { u32x4 w; w.x = pk2(a[0], a[1]); w.y = pk2(a[2], a[3]); w.z = pk2(b[0], b[1]); w.w = pk2(b[2], b[3]); *(u32x4*)p = w; }
;     __device__ __forceinline__ void operator()(ACC_T, const pg8::Unit& u, int wr, int wc, int fr, int fq) const {
;         const int row0 = u.pm * 256 + wr * 64 + fr, col0 = u.pn * 256 + wc * 32 + 8 * fq;
; #pragma unroll
;         for (int ai = 0; ai < 2; ++ai)
; #pragma unroll
;             for (int m = 0; m < 4; ++m) { const int row = row0 + ai * 128 + m * 16; const float* sp = ssq + tbase + row; const float rs = rsqrtf(((sp[0] + sp[TT]) + (sp[2 * TT] + sp[3 * TT])) * (1.f / 256.f) + EPS);
; #pragma unroll
;                 for (int bj = 0; bj < 2; ++bj) st8(O + (unsigned)row * (unsigned)ldc + col0 + bj * 128, acc[ai][bj][m][0] * rs, acc[ai][bj][m][1] * rs);
;                 asm volatile("" ::: "memory"); }
;     }
.LBB0_694:
	s_lshl_b32 s2, s84, 8
	v_mov_b32_e32 v0, v148
	v_mov_b32_e32 v138, v149
	s_add_i32 s2, s2, s66
	s_nop 0
	v_add_u32_e32 v146, s2, v0
	s_lshl_b32 s2, s85, 8
	s_or_b32 s2, s2, s67
	v_ashrrev_i32_e32 v147, 31, v146
	v_lshl_add_u32 v152, v138, 3, s2
	v_lshl_add_u64 v[138:139], v[146:147], 2, s[42:43]
	v_add_co_u32_e32 v140, vcc, s97, v138
	s_mov_b32 s2, 0xc0000
	s_nop 0
	v_addc_co_u32_e32 v141, vcc, 0, v139, vcc
	v_add_co_u32_e32 v142, vcc, s96, v138
	global_load_dword v154, v[138:139], off
	global_load_dword v156, v[140:141], off
	v_addc_co_u32_e32 v143, vcc, 0, v139, vcc
	v_add_co_u32_e32 v144, vcc, s2, v138
	global_load_dword v155, v[142:143], off
	s_nop 0
	v_addc_co_u32_e32 v145, vcc, 0, v139, vcc
	global_load_dword v157, v[144:145], off
	v_ashrrev_i32_e32 v153, 31, v152
	global_load_dword v160, v[138:139], off offset:64
	global_load_dword v162, v[140:141], off offset:64
	global_load_dword v161, v[142:143], off offset:64
	global_load_dword v163, v[144:145], off offset:64
	global_load_dword v164, v[138:139], off offset:128
	global_load_dword v166, v[140:141], off offset:128
	global_load_dword v165, v[142:143], off offset:128
	global_load_dword v167, v[144:145], off offset:128
	global_load_dword v168, v[138:139], off offset:192
	global_load_dword v170, v[140:141], off offset:192
	global_load_dword v169, v[142:143], off offset:192
	global_load_dword v171, v[144:145], off offset:192
	global_load_dword v172, v[138:139], off offset:512
	global_load_dword v174, v[140:141], off offset:512
	global_load_dword v173, v[142:143], off offset:512
	global_load_dword v175, v[144:145], off offset:512
	global_load_dword v176, v[138:139], off offset:576
	global_load_dword v178, v[140:141], off offset:576
	global_load_dword v177, v[142:143], off offset:576
	global_load_dword v179, v[144:145], off offset:576
	global_load_dword v180, v[138:139], off offset:640
	global_load_dword v182, v[140:141], off offset:640
	global_load_dword v181, v[142:143], off offset:640
	global_load_dword v183, v[144:145], off offset:640
	global_load_dword v184, v[138:139], off offset:704
	global_load_dword v186, v[140:141], off offset:704
	global_load_dword v185, v[142:143], off offset:704
	global_load_dword v187, v[144:145], off offset:704
	s_waitcnt vmcnt(28)
	v_pk_add_f32 v[154:155], v[154:155], v[156:157]
	s_nop 0
	v_add_f32_e32 v0, v154, v155
	v_fmamk_f32 v0, v0, 0x3b800000, v220
	v_cmp_gt_f32_e32 vcc, s51, v0
	v_mul_f32_e32 v147, 0x4b800000, v0
	s_nop 0
	v_cndmask_b32_e32 v0, v0, v147, vcc
	v_rsq_f32_e32 v0, v0
	s_nop 0
	v_mul_f32_e32 v147, 0x45800000, v0
	v_cndmask_b32_e32 v154, v0, v147, vcc
	v_lshlrev_b32_e32 v0, 10, v146
	v_lshl_add_u64 v[156:157], v[0:1], 1, s[6:7]
	v_lshlrev_b64 v[146:147], 1, v[152:153]
	v_lshl_add_u64 v[152:153], v[156:157], 0, v[146:147]
	v_pk_mul_f32 v[128:129], v[128:129], v[154:155] op_sel_hi:[1,0]
	v_pk_mul_f32 v[126:127], v[126:127], v[154:155] op_sel_hi:[1,0]
	v_pk_mul_f32 v[156:157], v[124:125], v[154:155] op_sel_hi:[1,0]
	v_pk_mul_f32 v[124:125], v[122:123], v[154:155] op_sel_hi:[1,0]
	v_cvt_pk_bf16_f32 v122, v126, v127
	v_cvt_pk_bf16_f32 v123, v128, v129
	v_cvt_pk_bf16_f32 v124, v124, v125
	v_cvt_pk_bf16_f32 v125, v156, v157
	global_store_dwordx4 v[152:153], v[122:125], off sc1
	v_pk_mul_f32 v[120:121], v[120:121], v[154:155] op_sel_hi:[1,0]
	v_pk_mul_f32 v[118:119], v[118:119], v[154:155] op_sel_hi:[1,0]
	v_pk_mul_f32 v[122:123], v[116:117], v[154:155] op_sel_hi:[1,0]
	v_pk_mul_f32 v[116:117], v[114:115], v[154:155] op_sel_hi:[1,0]
	v_cvt_pk_bf16_f32 v114, v118, v119
	v_cvt_pk_bf16_f32 v115, v120, v121
	v_cvt_pk_bf16_f32 v116, v116, v117
	v_cvt_pk_bf16_f32 v117, v122, v123
	global_store_dwordx4 v[152:153], v[114:117], off offset:256 sc1
	s_nop 1
	s_waitcnt vmcnt(26)
	v_pk_add_f32 v[114:115], v[160:161], v[162:163]
	s_nop 0
	v_add_f32_e32 v114, v114, v115
	v_fmamk_f32 v114, v114, 0x3b800000, v220
	v_cmp_gt_f32_e32 vcc, s51, v114
	v_mul_f32_e32 v115, 0x4b800000, v114
	v_add_u32_e32 v116, 0x4000, v0
	v_cndmask_b32_e32 v114, v114, v115, vcc
	v_rsq_f32_e32 v114, v114
	v_mov_b32_e32 v117, v1
	v_lshl_add_u64 v[116:117], v[116:117], 1, s[6:7]
	v_lshl_add_u64 v[116:117], v[116:117], 0, v[146:147]
	v_mul_f32_e32 v115, 0x45800000, v114
	v_cndmask_b32_e32 v114, v114, v115, vcc
	v_pk_mul_f32 v[112:113], v[112:113], v[114:115] op_sel_hi:[1,0]
	v_pk_mul_f32 v[110:111], v[110:111], v[114:115] op_sel_hi:[1,0]
	v_pk_mul_f32 v[118:119], v[108:109], v[114:115] op_sel_hi:[1,0]
	v_pk_mul_f32 v[108:109], v[106:107], v[114:115] op_sel_hi:[1,0]
	v_cvt_pk_bf16_f32 v106, v110, v111
	v_cvt_pk_bf16_f32 v107, v112, v113
	v_cvt_pk_bf16_f32 v108, v108, v109
	v_cvt_pk_bf16_f32 v109, v118, v119
	global_store_dwordx4 v[116:117], v[106:109], off sc1
	v_pk_mul_f32 v[104:105], v[104:105], v[114:115] op_sel_hi:[1,0]
	v_pk_mul_f32 v[102:103], v[102:103], v[114:115] op_sel_hi:[1,0]
	v_pk_mul_f32 v[106:107], v[100:101], v[114:115] op_sel_hi:[1,0]
	v_pk_mul_f32 v[100:101], v[98:99], v[114:115] op_sel_hi:[1,0]
	v_cvt_pk_bf16_f32 v98, v102, v103
	v_cvt_pk_bf16_f32 v99, v104, v105
	v_cvt_pk_bf16_f32 v100, v100, v101
	v_cvt_pk_bf16_f32 v101, v106, v107
	global_store_dwordx4 v[116:117], v[98:101], off offset:256 sc1
	s_nop 1
	s_waitcnt vmcnt(24)
; __device__ __forceinline__ void st8(bf16_t* p, f32x4 a, f32x4 b) { u32x4 w; w.x = pk2(a[0], a[1]); w.y = pk2(a[2], a[3]); w.z = pk2(b[0], b[1]); w.w = pk2(b[2], b[3]); *(u32x4*)p = w; }
;     __device__ __forceinline__ void operator()(ACC_T, const pg8::Unit& u, int wr, int wc, int fr, int fq) const {
;         const int row0 = u.pm * 256 + wr * 64 + fr, col0 = u.pn * 256 + wc * 32 + 8 * fq;
; #pragma unroll
;         for (int ai = 0; ai < 2; ++ai)
; #pragma unroll
;             for (int m = 0; m < 4; ++m) { const int row = row0 + ai * 128 + m * 16; const float* sp = ssq + tbase + row; const float rs = rsqrtf(((sp[0] + sp[TT]) + (sp[2 * TT] + sp[3 * TT])) * (1.f / 256.f) + EPS);
; #pragma unroll
;                 for (int bj = 0; bj < 2; ++bj) st8(O + (unsigned)row * (unsigned)ldc + col0 + bj * 128, acc[ai][bj][m][0] * rs, acc[ai][bj][m][1] * rs);
;                 asm volatile("" ::: "memory"); }
;     }
	v_pk_add_f32 v[98:99], v[164:165], v[166:167]
	s_nop 0
	v_add_f32_e32 v98, v98, v99
	v_fmamk_f32 v98, v98, 0x3b800000, v220
	v_cmp_gt_f32_e32 vcc, s51, v98
	v_mul_f32_e32 v99, 0x4b800000, v98
	v_add_u32_e32 v100, 0x8000, v0
	v_cndmask_b32_e32 v98, v98, v99, vcc
	v_rsq_f32_e32 v98, v98
	v_mov_b32_e32 v101, v1
	v_lshl_add_u64 v[100:101], v[100:101], 1, s[6:7]
	v_lshl_add_u64 v[100:101], v[100:101], 0, v[146:147]
	v_mul_f32_e32 v99, 0x45800000, v98
	v_cndmask_b32_e32 v98, v98, v99, vcc
	v_pk_mul_f32 v[96:97], v[96:97], v[98:99] op_sel_hi:[1,0]
	v_pk_mul_f32 v[94:95], v[94:95], v[98:99] op_sel_hi:[1,0]
	v_pk_mul_f32 v[102:103], v[92:93], v[98:99] op_sel_hi:[1,0]
	v_pk_mul_f32 v[92:93], v[90:91], v[98:99] op_sel_hi:[1,0]
	v_cvt_pk_bf16_f32 v90, v94, v95
	v_cvt_pk_bf16_f32 v91, v96, v97
	v_cvt_pk_bf16_f32 v92, v92, v93
	v_cvt_pk_bf16_f32 v93, v102, v103
	global_store_dwordx4 v[100:101], v[90:93], off sc1
	v_pk_mul_f32 v[88:89], v[88:89], v[98:99] op_sel_hi:[1,0]
	v_pk_mul_f32 v[86:87], v[86:87], v[98:99] op_sel_hi:[1,0]
	v_pk_mul_f32 v[90:91], v[84:85], v[98:99] op_sel_hi:[1,0]
	v_pk_mul_f32 v[84:85], v[82:83], v[98:99] op_sel_hi:[1,0]
	v_cvt_pk_bf16_f32 v82, v86, v87
	v_cvt_pk_bf16_f32 v83, v88, v89
	v_cvt_pk_bf16_f32 v84, v84, v85
	v_cvt_pk_bf16_f32 v85, v90, v91
	global_store_dwordx4 v[100:101], v[82:85], off offset:256 sc1
	s_nop 1
	s_waitcnt vmcnt(22)
	v_pk_add_f32 v[82:83], v[168:169], v[170:171]
	s_nop 0
	v_add_f32_e32 v82, v82, v83
	v_fmamk_f32 v82, v82, 0x3b800000, v220
	v_cmp_gt_f32_e32 vcc, s51, v82
	v_mul_f32_e32 v83, 0x4b800000, v82
	v_add_u32_e32 v84, 0xc000, v0
	v_cndmask_b32_e32 v82, v82, v83, vcc
	v_rsq_f32_e32 v82, v82
	v_mov_b32_e32 v85, v1
	v_lshl_add_u64 v[84:85], v[84:85], 1, s[6:7]
	v_lshl_add_u64 v[84:85], v[84:85], 0, v[146:147]
	v_mul_f32_e32 v83, 0x45800000, v82
	v_cndmask_b32_e32 v82, v82, v83, vcc
	v_pk_mul_f32 v[80:81], v[80:81], v[82:83] op_sel_hi:[1,0]
	v_pk_mul_f32 v[78:79], v[78:79], v[82:83] op_sel_hi:[1,0]
	v_pk_mul_f32 v[86:87], v[76:77], v[82:83] op_sel_hi:[1,0]
	v_pk_mul_f32 v[76:77], v[74:75], v[82:83] op_sel_hi:[1,0]
	v_cvt_pk_bf16_f32 v74, v78, v79
	v_cvt_pk_bf16_f32 v75, v80, v81
	v_cvt_pk_bf16_f32 v76, v76, v77
	v_cvt_pk_bf16_f32 v77, v86, v87
	global_store_dwordx4 v[84:85], v[74:77], off sc1
	v_pk_mul_f32 v[72:73], v[72:73], v[82:83] op_sel_hi:[1,0]
	v_pk_mul_f32 v[70:71], v[70:71], v[82:83] op_sel_hi:[1,0]
	v_pk_mul_f32 v[74:75], v[68:69], v[82:83] op_sel_hi:[1,0]
	v_pk_mul_f32 v[68:69], v[66:67], v[82:83] op_sel_hi:[1,0]
	v_cvt_pk_bf16_f32 v66, v70, v71
	v_cvt_pk_bf16_f32 v67, v72, v73
	v_cvt_pk_bf16_f32 v68, v68, v69
	v_cvt_pk_bf16_f32 v69, v74, v75
	global_store_dwordx4 v[84:85], v[66:69], off offset:256 sc1
	s_nop 1
	s_waitcnt vmcnt(20)
	v_pk_add_f32 v[66:67], v[172:173], v[174:175]
	s_nop 0
	v_add_f32_e32 v66, v66, v67
	v_fmamk_f32 v66, v66, 0x3b800000, v220
	v_cmp_gt_f32_e32 vcc, s51, v66
	v_mul_f32_e32 v67, 0x4b800000, v66
	v_add_u32_e32 v68, 0x20000, v0
	v_cndmask_b32_e32 v66, v66, v67, vcc
	v_rsq_f32_e32 v66, v66
	v_mov_b32_e32 v69, v1
	v_lshl_add_u64 v[68:69], v[68:69], 1, s[6:7]
	v_lshl_add_u64 v[68:69], v[68:69], 0, v[146:147]
	v_mul_f32_e32 v67, 0x45800000, v66
	v_cndmask_b32_e32 v66, v66, v67, vcc
	v_pk_mul_f32 v[64:65], v[64:65], v[66:67] op_sel_hi:[1,0]
	v_pk_mul_f32 v[62:63], v[62:63], v[66:67] op_sel_hi:[1,0]
	v_pk_mul_f32 v[70:71], v[60:61], v[66:67] op_sel_hi:[1,0]
	v_pk_mul_f32 v[60:61], v[58:59], v[66:67] op_sel_hi:[1,0]
	v_cvt_pk_bf16_f32 v58, v62, v63
	v_cvt_pk_bf16_f32 v59, v64, v65
	v_cvt_pk_bf16_f32 v60, v60, v61
	v_cvt_pk_bf16_f32 v61, v70, v71
	global_store_dwordx4 v[68:69], v[58:61], off sc1
	v_pk_mul_f32 v[56:57], v[56:57], v[66:67] op_sel_hi:[1,0]
	v_pk_mul_f32 v[54:55], v[54:55], v[66:67] op_sel_hi:[1,0]
	v_pk_mul_f32 v[58:59], v[52:53], v[66:67] op_sel_hi:[1,0]
	v_pk_mul_f32 v[52:53], v[50:51], v[66:67] op_sel_hi:[1,0]
	v_cvt_pk_bf16_f32 v50, v54, v55
	v_cvt_pk_bf16_f32 v51, v56, v57
	v_cvt_pk_bf16_f32 v52, v52, v53
	v_cvt_pk_bf16_f32 v53, v58, v59
	global_store_dwordx4 v[68:69], v[50:53], off offset:256 sc1
	s_nop 1
	s_waitcnt vmcnt(18)
; __device__ __forceinline__ void st8(bf16_t* p, f32x4 a, f32x4 b) { u32x4 w; w.x = pk2(a[0], a[1]); w.y = pk2(a[2], a[3]); w.z = pk2(b[0], b[1]); w.w = pk2(b[2], b[3]); *(u32x4*)p = w; }
;     __device__ __forceinline__ void operator()(ACC_T, const pg8::Unit& u, int wr, int wc, int fr, int fq) const {
;         const int row0 = u.pm * 256 + wr * 64 + fr, col0 = u.pn * 256 + wc * 32 + 8 * fq;
; #pragma unroll
;         for (int ai = 0; ai < 2; ++ai)
; #pragma unroll
;             for (int m = 0; m < 4; ++m) { const int row = row0 + ai * 128 + m * 16; const float* sp = ssq + tbase + row; const float rs = rsqrtf(((sp[0] + sp[TT]) + (sp[2 * TT] + sp[3 * TT])) * (1.f / 256.f) + EPS);
; #pragma unroll
;                 for (int bj = 0; bj < 2; ++bj) st8(O + (unsigned)row * (unsigned)ldc + col0 + bj * 128, acc[ai][bj][m][0] * rs, acc[ai][bj][m][1] * rs);
;                 asm volatile("" ::: "memory"); }
;     }
	v_pk_add_f32 v[50:51], v[176:177], v[178:179]
	s_nop 0
	v_add_f32_e32 v50, v50, v51
	v_fmamk_f32 v50, v50, 0x3b800000, v220
	v_cmp_gt_f32_e32 vcc, s51, v50
	v_mul_f32_e32 v51, 0x4b800000, v50
	v_add_u32_e32 v52, 0x24000, v0
	v_cndmask_b32_e32 v50, v50, v51, vcc
	v_rsq_f32_e32 v50, v50
	v_mov_b32_e32 v53, v1
	v_lshl_add_u64 v[52:53], v[52:53], 1, s[6:7]
	v_lshl_add_u64 v[52:53], v[52:53], 0, v[146:147]
	v_mul_f32_e32 v51, 0x45800000, v50
	v_cndmask_b32_e32 v50, v50, v51, vcc
	v_pk_mul_f32 v[48:49], v[48:49], v[50:51] op_sel_hi:[1,0]
	v_pk_mul_f32 v[46:47], v[46:47], v[50:51] op_sel_hi:[1,0]
	v_pk_mul_f32 v[54:55], v[44:45], v[50:51] op_sel_hi:[1,0]
	v_pk_mul_f32 v[44:45], v[42:43], v[50:51] op_sel_hi:[1,0]
	v_cvt_pk_bf16_f32 v42, v46, v47
	v_cvt_pk_bf16_f32 v43, v48, v49
	v_cvt_pk_bf16_f32 v44, v44, v45
	v_cvt_pk_bf16_f32 v45, v54, v55
	global_store_dwordx4 v[52:53], v[42:45], off sc1
	v_pk_mul_f32 v[40:41], v[40:41], v[50:51] op_sel_hi:[1,0]
	v_pk_mul_f32 v[38:39], v[38:39], v[50:51] op_sel_hi:[1,0]
	v_pk_mul_f32 v[42:43], v[36:37], v[50:51] op_sel_hi:[1,0]
	v_pk_mul_f32 v[36:37], v[34:35], v[50:51] op_sel_hi:[1,0]
	v_cvt_pk_bf16_f32 v34, v38, v39
	v_cvt_pk_bf16_f32 v35, v40, v41
	v_cvt_pk_bf16_f32 v36, v36, v37
	v_cvt_pk_bf16_f32 v37, v42, v43
	global_store_dwordx4 v[52:53], v[34:37], off offset:256 sc1
	s_nop 1
	s_waitcnt vmcnt(16)
	v_pk_add_f32 v[34:35], v[180:181], v[182:183]
	s_nop 0
	v_add_f32_e32 v34, v34, v35
	v_fmamk_f32 v34, v34, 0x3b800000, v220
	v_cmp_gt_f32_e32 vcc, s51, v34
	v_mul_f32_e32 v35, 0x4b800000, v34
	v_add_u32_e32 v36, 0x28000, v0
	v_cndmask_b32_e32 v34, v34, v35, vcc
	v_rsq_f32_e32 v34, v34
	v_mov_b32_e32 v37, v1
	v_lshl_add_u64 v[36:37], v[36:37], 1, s[6:7]
	v_lshl_add_u64 v[36:37], v[36:37], 0, v[146:147]
	v_mul_f32_e32 v35, 0x45800000, v34
	v_cndmask_b32_e32 v34, v34, v35, vcc
	v_pk_mul_f32 v[32:33], v[32:33], v[34:35] op_sel_hi:[1,0]
	v_pk_mul_f32 v[30:31], v[30:31], v[34:35] op_sel_hi:[1,0]
	v_pk_mul_f32 v[38:39], v[28:29], v[34:35] op_sel_hi:[1,0]
	v_pk_mul_f32 v[28:29], v[26:27], v[34:35] op_sel_hi:[1,0]
	v_cvt_pk_bf16_f32 v26, v30, v31
	v_cvt_pk_bf16_f32 v27, v32, v33
	v_cvt_pk_bf16_f32 v28, v28, v29
	v_cvt_pk_bf16_f32 v29, v38, v39
	global_store_dwordx4 v[36:37], v[26:29], off sc1
	v_pk_mul_f32 v[24:25], v[24:25], v[34:35] op_sel_hi:[1,0]
	v_pk_mul_f32 v[22:23], v[22:23], v[34:35] op_sel_hi:[1,0]
	v_pk_mul_f32 v[26:27], v[20:21], v[34:35] op_sel_hi:[1,0]
	v_pk_mul_f32 v[20:21], v[18:19], v[34:35] op_sel_hi:[1,0]
	v_cvt_pk_bf16_f32 v18, v22, v23
	v_cvt_pk_bf16_f32 v19, v24, v25
	v_cvt_pk_bf16_f32 v20, v20, v21
	v_cvt_pk_bf16_f32 v21, v26, v27
	global_store_dwordx4 v[36:37], v[18:21], off offset:256 sc1
	v_add_u32_e32 v0, 0x2c000, v0
	s_nop 1
	s_waitcnt vmcnt(14)
	v_pk_add_f32 v[18:19], v[184:185], v[186:187]
	s_nop 0
	v_add_f32_e32 v18, v18, v19
	v_fmamk_f32 v18, v18, 0x3b800000, v220
	v_cmp_gt_f32_e32 vcc, s51, v18
	v_mul_f32_e32 v19, 0x4b800000, v18
	v_lshl_add_u64 v[20:21], v[0:1], 1, s[6:7]
	v_cndmask_b32_e32 v18, v18, v19, vcc
	v_rsq_f32_e32 v18, v18
	v_lshl_add_u64 v[20:21], v[20:21], 0, v[146:147]
	v_mul_f32_e32 v19, 0x45800000, v18
	v_cndmask_b32_e32 v18, v18, v19, vcc
	v_pk_mul_f32 v[16:17], v[16:17], v[18:19] op_sel_hi:[1,0]
	v_pk_mul_f32 v[14:15], v[14:15], v[18:19] op_sel_hi:[1,0]
	v_pk_mul_f32 v[22:23], v[12:13], v[18:19] op_sel_hi:[1,0]
	v_pk_mul_f32 v[12:13], v[10:11], v[18:19] op_sel_hi:[1,0]
	v_cvt_pk_bf16_f32 v10, v14, v15
	v_cvt_pk_bf16_f32 v11, v16, v17
	v_cvt_pk_bf16_f32 v12, v12, v13
	v_cvt_pk_bf16_f32 v13, v22, v23
	global_store_dwordx4 v[20:21], v[10:13], off sc1
	v_pk_mul_f32 v[8:9], v[8:9], v[18:19] op_sel_hi:[1,0]
	v_pk_mul_f32 v[6:7], v[6:7], v[18:19] op_sel_hi:[1,0]
	v_pk_mul_f32 v[10:11], v[4:5], v[18:19] op_sel_hi:[1,0]
	v_pk_mul_f32 v[4:5], v[2:3], v[18:19] op_sel_hi:[1,0]
	v_cvt_pk_bf16_f32 v2, v6, v7
	v_cvt_pk_bf16_f32 v3, v8, v9
	v_cvt_pk_bf16_f32 v4, v4, v5
	v_cvt_pk_bf16_f32 v5, v10, v11
	global_store_dwordx4 v[20:21], v[2:5], off offset:256 sc1
	s_andn2_b64 vcc, exec, s[38:39]
	s_cbranch_vccnz .LBB0_683
	s_andn2_b64 vcc, exec, s[4:5]
	s_cbranch_vccnz .LBB0_682
	s_barrier
	s_branch .LBB0_682

; __device__ __forceinline__ void st8(bf16_t* p, f32x4 a, f32x4 b) { u32x4 w; w.x = pk2(a[0], a[1]); w.y = pk2(a[2], a[3]); w.z = pk2(b[0], b[1]); w.w = pk2(b[2], b[3]); *(u32x4*)p = w; }
; __device__ __forceinline__ void ld8(const bf16_t* p, f32x4& a, f32x4& b) { const u32x4 w = *(const u32x4*)p; a[0] = bflo(w.x); a[1] = bfhi(w.x); a[2] = bflo(w.y); a[3] = bfhi(w.y); b[0] = bflo(w.z); b[1] = bfhi(w.z); b[2] = bflo(w.w); b[3] = bfhi(w.w); }
;     __device__ __forceinline__ void operator()(ACC_T, const pg8::Unit& u, int wr, int wc, int fr, int fq) const {
;         const int row0 = u.pm * 256 + wr * 64 + fr, col0 = u.pn * 256 + wc * 32 + 8 * fq;
; #pragma unroll
;         for (int ai = 0; ai < 2; ++ai)
; #pragma unroll
;             for (int m = 0; m < 4; ++m) { const int row = row0 + ai * 128 + m * 16;
; #pragma unroll
;                 for (int bj = 0; bj < 2; ++bj) { const unsigned off = (unsigned)row * 1024u + col0 + bj * 128; f32x4 g0, g1; ld8(G + off, g0, g1);
;                     f32x4 v0 = acc[ai][bj][m][0] * g0, v1 = acc[ai][bj][m][1] * g1;
;                     if (MODE == 1) { f32x4 p0, p1; ld8(P + off, p0, p1); v0 += p0; v1 += p1; }
;                     st8(O + off, v0, v1); }
;                 asm volatile("" ::: "memory"); }
;     }
.LBB0_1065:
	v_mov_b32_e32 v0, v143
	v_mov_b32_e32 v146, v142
	s_lshl_b32 s2, s86, 8
	s_add_i32 s2, s2, s45
	s_lshl_b32 s8, s68, 8
	v_lshlrev_b32_e32 v0, 3, v0
	v_add_lshl_u32 v146, s2, v146, 10
	s_or_b32 s2, s8, s60
	v_add3_u32 v0, s2, v0, v146
	v_lshlrev_b64 v[150:151], 1, v[0:1]
	v_mov_b32_e32 v164, v0
	v_mov_b32_e32 v165, v1
	v_lshlrev_b64 v[164:165], 1, v[164:165]
	v_lshl_add_u64 v[168:169], s[42:43], 0, v[164:165]
	v_lshl_add_u64 v[164:165], s[40:41], 0, v[164:165]
	global_load_dwordx4 v[164:167], v[164:165], off
	global_load_dwordx4 v[168:171], v[168:169], off
	v_add_u32_e32 v172, 0x80, v0
	v_mov_b32_e32 v173, v1
	v_lshlrev_b64 v[172:173], 1, v[172:173]
	v_lshl_add_u64 v[176:177], s[42:43], 0, v[172:173]
	v_lshl_add_u64 v[172:173], s[40:41], 0, v[172:173]
	global_load_dwordx4 v[172:175], v[172:173], off
	global_load_dwordx4 v[176:179], v[176:177], off
	v_add_u32_e32 v180, 0x4000, v0
	v_mov_b32_e32 v181, v1
	v_lshlrev_b64 v[180:181], 1, v[180:181]
	v_lshl_add_u64 v[184:185], s[42:43], 0, v[180:181]
	v_lshl_add_u64 v[180:181], s[40:41], 0, v[180:181]
	global_load_dwordx4 v[180:183], v[180:181], off
	global_load_dwordx4 v[184:187], v[184:185], off
	v_add_u32_e32 v188, 0x4080, v0
	v_mov_b32_e32 v189, v1
	v_lshlrev_b64 v[188:189], 1, v[188:189]
	v_lshl_add_u64 v[192:193], s[42:43], 0, v[188:189]
	v_lshl_add_u64 v[188:189], s[40:41], 0, v[188:189]
	global_load_dwordx4 v[188:191], v[188:189], off
	global_load_dwordx4 v[192:195], v[192:193], off
	v_add_u32_e32 v196, 0x8000, v0
	v_mov_b32_e32 v197, v1
	v_lshlrev_b64 v[196:197], 1, v[196:197]
	v_lshl_add_u64 v[200:201], s[42:43], 0, v[196:197]
	v_lshl_add_u64 v[196:197], s[40:41], 0, v[196:197]
	global_load_dwordx4 v[196:199], v[196:197], off
	global_load_dwordx4 v[200:203], v[200:201], off
	v_add_u32_e32 v204, 0x8080, v0
	v_mov_b32_e32 v205, v1
	v_lshlrev_b64 v[204:205], 1, v[204:205]
	v_lshl_add_u64 v[208:209], s[42:43], 0, v[204:205]
	v_lshl_add_u64 v[204:205], s[40:41], 0, v[204:205]
	global_load_dwordx4 v[204:207], v[204:205], off
	global_load_dwordx4 v[208:211], v[208:209], off
	v_add_u32_e32 v212, 0xc000, v0
	v_mov_b32_e32 v213, v1
	v_lshlrev_b64 v[212:213], 1, v[212:213]
	v_lshl_add_u64 v[216:217], s[42:43], 0, v[212:213]
	v_lshl_add_u64 v[212:213], s[40:41], 0, v[212:213]
	global_load_dwordx4 v[212:215], v[212:213], off
	global_load_dwordx4 v[216:219], v[216:217], off
	s_waitcnt vmcnt(12)
	v_lshlrev_b32_e32 v152, 16, v164
	v_and_b32_e32 v153, 0xffff0000, v164
	v_lshlrev_b32_e32 v154, 16, v165
	v_and_b32_e32 v155, 0xffff0000, v165
	v_lshlrev_b32_e32 v156, 16, v166
	v_and_b32_e32 v157, 0xffff0000, v166
	v_lshlrev_b32_e32 v158, 16, v167
	v_and_b32_e32 v159, 0xffff0000, v167
	v_lshlrev_b32_e32 v160, 16, v168
	v_and_b32_e32 v161, 0xffff0000, v168
	v_lshlrev_b32_e32 v146, 16, v169
	v_and_b32_e32 v147, 0xffff0000, v169
	v_lshlrev_b32_e32 v162, 16, v170
	v_and_b32_e32 v163, 0xffff0000, v170
	v_lshlrev_b32_e32 v148, 16, v171
	v_and_b32_e32 v149, 0xffff0000, v171
	v_pk_fma_f32 v[128:129], v[128:129], v[154:155], v[146:147]
	v_pk_fma_f32 v[126:127], v[126:127], v[152:153], v[160:161]
	v_pk_fma_f32 v[146:147], v[124:125], v[158:159], v[148:149]
	v_pk_fma_f32 v[124:125], v[122:123], v[156:157], v[162:163]
	v_lshl_add_u64 v[148:149], s[6:7], 0, v[150:151]
	v_cvt_pk_bf16_f32 v122, v126, v127
	v_cvt_pk_bf16_f32 v123, v128, v129
	v_cvt_pk_bf16_f32 v124, v124, v125
	v_cvt_pk_bf16_f32 v125, v146, v147
	global_store_dwordx4 v[148:149], v[122:125], off sc1
	s_nop 1
	v_add_u32_e32 v122, 0x80, v0
	v_mov_b32_e32 v123, v1
	v_lshlrev_b64 v[126:127], 1, v[122:123]
	s_waitcnt vmcnt(11)
	v_lshlrev_b32_e32 v128, 16, v172
	v_and_b32_e32 v129, 0xffff0000, v172
	v_lshlrev_b32_e32 v146, 16, v173
	v_and_b32_e32 v147, 0xffff0000, v173
	v_lshlrev_b32_e32 v148, 16, v174
	v_and_b32_e32 v149, 0xffff0000, v174
	v_lshlrev_b32_e32 v150, 16, v175
	v_and_b32_e32 v151, 0xffff0000, v175
	v_lshlrev_b32_e32 v152, 16, v176
	v_and_b32_e32 v153, 0xffff0000, v176
	v_lshlrev_b32_e32 v122, 16, v177
	v_and_b32_e32 v123, 0xffff0000, v177
	v_lshlrev_b32_e32 v154, 16, v178
	v_and_b32_e32 v155, 0xffff0000, v178
	v_lshlrev_b32_e32 v124, 16, v179
	v_and_b32_e32 v125, 0xffff0000, v179
	v_pk_fma_f32 v[120:121], v[120:121], v[146:147], v[122:123]
	v_pk_fma_f32 v[118:119], v[118:119], v[128:129], v[152:153]
	v_pk_fma_f32 v[122:123], v[116:117], v[150:151], v[124:125]
	v_pk_fma_f32 v[116:117], v[114:115], v[148:149], v[154:155]
	v_lshl_add_u64 v[124:125], s[6:7], 0, v[126:127]
	v_cvt_pk_bf16_f32 v114, v118, v119
	v_cvt_pk_bf16_f32 v115, v120, v121
	v_cvt_pk_bf16_f32 v116, v116, v117
	v_cvt_pk_bf16_f32 v117, v122, v123
	global_store_dwordx4 v[124:125], v[114:117], off sc1
	s_nop 1
	v_add_u32_e32 v114, 0x4000, v0
	v_mov_b32_e32 v115, v1
	v_lshlrev_b64 v[118:119], 1, v[114:115]
	s_waitcnt vmcnt(10)
	v_lshlrev_b32_e32 v120, 16, v180
	v_and_b32_e32 v121, 0xffff0000, v180
	v_lshlrev_b32_e32 v122, 16, v181
	v_and_b32_e32 v123, 0xffff0000, v181
	v_lshlrev_b32_e32 v124, 16, v182
	v_and_b32_e32 v125, 0xffff0000, v182
	v_lshlrev_b32_e32 v126, 16, v183
	v_and_b32_e32 v127, 0xffff0000, v183
	v_lshlrev_b32_e32 v128, 16, v184
	v_and_b32_e32 v129, 0xffff0000, v184
	v_lshlrev_b32_e32 v114, 16, v185
	v_and_b32_e32 v115, 0xffff0000, v185
	v_lshlrev_b32_e32 v146, 16, v186
	v_and_b32_e32 v147, 0xffff0000, v186
	v_lshlrev_b32_e32 v116, 16, v187
	v_and_b32_e32 v117, 0xffff0000, v187
	v_pk_fma_f32 v[112:113], v[112:113], v[122:123], v[114:115]
	v_pk_fma_f32 v[110:111], v[110:111], v[120:121], v[128:129]
	v_pk_fma_f32 v[114:115], v[108:109], v[126:127], v[116:117]
	v_pk_fma_f32 v[108:109], v[106:107], v[124:125], v[146:147]
	v_lshl_add_u64 v[116:117], s[6:7], 0, v[118:119]
	v_cvt_pk_bf16_f32 v106, v110, v111
	v_cvt_pk_bf16_f32 v107, v112, v113
	v_cvt_pk_bf16_f32 v108, v108, v109
	v_cvt_pk_bf16_f32 v109, v114, v115
	global_store_dwordx4 v[116:117], v[106:109], off sc1
	s_nop 1
	v_add_u32_e32 v106, 0x4080, v0
	v_mov_b32_e32 v107, v1
	v_lshlrev_b64 v[110:111], 1, v[106:107]
	s_waitcnt vmcnt(9)
; __device__ __forceinline__ void st8(bf16_t* p, f32x4 a, f32x4 b) { u32x4 w; w.x = pk2(a[0], a[1]); w.y = pk2(a[2], a[3]); w.z = pk2(b[0], b[1]); w.w = pk2(b[2], b[3]); *(u32x4*)p = w; }
; __device__ __forceinline__ void ld8(const bf16_t* p, f32x4& a, f32x4& b) { const u32x4 w = *(const u32x4*)p; a[0] = bflo(w.x); a[1] = bfhi(w.x); a[2] = bflo(w.y); a[3] = bfhi(w.y); b[0] = bflo(w.z); b[1] = bfhi(w.z); b[2] = bflo(w.w); b[3] = bfhi(w.w); }
;     __device__ __forceinline__ void operator()(ACC_T, const pg8::Unit& u, int wr, int wc, int fr, int fq) const {
;         const int row0 = u.pm * 256 + wr * 64 + fr, col0 = u.pn * 256 + wc * 32 + 8 * fq;
; #pragma unroll
;         for (int ai = 0; ai < 2; ++ai)
; #pragma unroll
;             for (int m = 0; m < 4; ++m) { const int row = row0 + ai * 128 + m * 16;
; #pragma unroll
;                 for (int bj = 0; bj < 2; ++bj) { const unsigned off = (unsigned)row * 1024u + col0 + bj * 128; f32x4 g0, g1; ld8(G + off, g0, g1);
;                     f32x4 v0 = acc[ai][bj][m][0] * g0, v1 = acc[ai][bj][m][1] * g1;
;                     if (MODE == 1) { f32x4 p0, p1; ld8(P + off, p0, p1); v0 += p0; v1 += p1; }
;                     st8(O + off, v0, v1); }
;                 asm volatile("" ::: "memory"); }
;     }
	v_lshlrev_b32_e32 v112, 16, v188
	v_and_b32_e32 v113, 0xffff0000, v188
	v_lshlrev_b32_e32 v114, 16, v189
	v_and_b32_e32 v115, 0xffff0000, v189
	v_lshlrev_b32_e32 v116, 16, v190
	v_and_b32_e32 v117, 0xffff0000, v190
	v_lshlrev_b32_e32 v118, 16, v191
	v_and_b32_e32 v119, 0xffff0000, v191
	v_lshlrev_b32_e32 v120, 16, v192
	v_and_b32_e32 v121, 0xffff0000, v192
	v_lshlrev_b32_e32 v106, 16, v193
	v_and_b32_e32 v107, 0xffff0000, v193
	v_lshlrev_b32_e32 v122, 16, v194
	v_and_b32_e32 v123, 0xffff0000, v194
	v_lshlrev_b32_e32 v108, 16, v195
	v_and_b32_e32 v109, 0xffff0000, v195
	v_pk_fma_f32 v[104:105], v[104:105], v[114:115], v[106:107]
	v_pk_fma_f32 v[102:103], v[102:103], v[112:113], v[120:121]
	v_pk_fma_f32 v[106:107], v[100:101], v[118:119], v[108:109]
	v_pk_fma_f32 v[100:101], v[98:99], v[116:117], v[122:123]
	v_lshl_add_u64 v[108:109], s[6:7], 0, v[110:111]
	v_cvt_pk_bf16_f32 v98, v102, v103
	v_cvt_pk_bf16_f32 v99, v104, v105
	v_cvt_pk_bf16_f32 v100, v100, v101
	v_cvt_pk_bf16_f32 v101, v106, v107
	global_store_dwordx4 v[108:109], v[98:101], off sc1
	s_nop 1
	v_add_u32_e32 v98, 0x8000, v0
	v_mov_b32_e32 v99, v1
	v_lshlrev_b64 v[102:103], 1, v[98:99]
	s_waitcnt vmcnt(8)
	v_lshlrev_b32_e32 v104, 16, v196
	v_and_b32_e32 v105, 0xffff0000, v196
	v_lshlrev_b32_e32 v106, 16, v197
	v_and_b32_e32 v107, 0xffff0000, v197
	v_lshlrev_b32_e32 v108, 16, v198
	v_and_b32_e32 v109, 0xffff0000, v198
	v_lshlrev_b32_e32 v110, 16, v199
	v_and_b32_e32 v111, 0xffff0000, v199
	v_lshlrev_b32_e32 v112, 16, v200
	v_and_b32_e32 v113, 0xffff0000, v200
	v_lshlrev_b32_e32 v98, 16, v201
	v_and_b32_e32 v99, 0xffff0000, v201
	v_lshlrev_b32_e32 v114, 16, v202
	v_and_b32_e32 v115, 0xffff0000, v202
	v_lshlrev_b32_e32 v100, 16, v203
	v_and_b32_e32 v101, 0xffff0000, v203
	v_pk_fma_f32 v[96:97], v[96:97], v[106:107], v[98:99]
	v_pk_fma_f32 v[94:95], v[94:95], v[104:105], v[112:113]
	v_pk_fma_f32 v[98:99], v[92:93], v[110:111], v[100:101]
	v_pk_fma_f32 v[92:93], v[90:91], v[108:109], v[114:115]
	v_lshl_add_u64 v[100:101], s[6:7], 0, v[102:103]
	v_cvt_pk_bf16_f32 v90, v94, v95
	v_cvt_pk_bf16_f32 v91, v96, v97
	v_cvt_pk_bf16_f32 v92, v92, v93
	v_cvt_pk_bf16_f32 v93, v98, v99
	global_store_dwordx4 v[100:101], v[90:93], off sc1
	s_nop 1
	v_add_u32_e32 v90, 0x8080, v0
	v_mov_b32_e32 v91, v1
	v_lshlrev_b64 v[94:95], 1, v[90:91]
	s_waitcnt vmcnt(7)
	v_lshlrev_b32_e32 v96, 16, v204
	v_and_b32_e32 v97, 0xffff0000, v204
	v_lshlrev_b32_e32 v98, 16, v205
	v_and_b32_e32 v99, 0xffff0000, v205
	v_lshlrev_b32_e32 v100, 16, v206
	v_and_b32_e32 v101, 0xffff0000, v206
	v_lshlrev_b32_e32 v102, 16, v207
	v_and_b32_e32 v103, 0xffff0000, v207
	v_lshlrev_b32_e32 v104, 16, v208
	v_and_b32_e32 v105, 0xffff0000, v208
	v_lshlrev_b32_e32 v90, 16, v209
	v_and_b32_e32 v91, 0xffff0000, v209
	v_lshlrev_b32_e32 v106, 16, v210
	v_and_b32_e32 v107, 0xffff0000, v210
	v_lshlrev_b32_e32 v92, 16, v211
	v_and_b32_e32 v93, 0xffff0000, v211
	v_pk_fma_f32 v[88:89], v[88:89], v[98:99], v[90:91]
	v_pk_fma_f32 v[86:87], v[86:87], v[96:97], v[104:105]
	v_pk_fma_f32 v[90:91], v[84:85], v[102:103], v[92:93]
	v_pk_fma_f32 v[84:85], v[82:83], v[100:101], v[106:107]
	v_lshl_add_u64 v[92:93], s[6:7], 0, v[94:95]
	v_cvt_pk_bf16_f32 v82, v86, v87
	v_cvt_pk_bf16_f32 v83, v88, v89
	v_cvt_pk_bf16_f32 v84, v84, v85
	v_cvt_pk_bf16_f32 v85, v90, v91
	global_store_dwordx4 v[92:93], v[82:85], off sc1
	s_nop 1
	v_add_u32_e32 v82, 0xc000, v0
	v_mov_b32_e32 v83, v1
	v_lshlrev_b64 v[86:87], 1, v[82:83]
	s_waitcnt vmcnt(6)
	v_lshlrev_b32_e32 v88, 16, v212
	v_and_b32_e32 v89, 0xffff0000, v212
	v_lshlrev_b32_e32 v90, 16, v213
	v_and_b32_e32 v91, 0xffff0000, v213
	v_lshlrev_b32_e32 v92, 16, v214
	v_and_b32_e32 v93, 0xffff0000, v214
	v_lshlrev_b32_e32 v94, 16, v215
	v_and_b32_e32 v95, 0xffff0000, v215
	v_lshlrev_b32_e32 v96, 16, v216
	v_and_b32_e32 v97, 0xffff0000, v216
	v_lshlrev_b32_e32 v82, 16, v217
	v_and_b32_e32 v83, 0xffff0000, v217
	v_lshlrev_b32_e32 v98, 16, v218
	v_and_b32_e32 v99, 0xffff0000, v218
	v_lshlrev_b32_e32 v84, 16, v219
	v_and_b32_e32 v85, 0xffff0000, v219
	v_pk_fma_f32 v[80:81], v[80:81], v[90:91], v[82:83]
	v_pk_fma_f32 v[78:79], v[78:79], v[88:89], v[96:97]
	v_pk_fma_f32 v[82:83], v[76:77], v[94:95], v[84:85]
	v_pk_fma_f32 v[76:77], v[74:75], v[92:93], v[98:99]
	v_lshl_add_u64 v[84:85], s[6:7], 0, v[86:87]
	v_cvt_pk_bf16_f32 v74, v78, v79
	v_cvt_pk_bf16_f32 v75, v80, v81
	v_cvt_pk_bf16_f32 v76, v76, v77
	v_cvt_pk_bf16_f32 v77, v82, v83
	global_store_dwordx4 v[84:85], v[74:77], off sc1
	s_nop 1
	v_add_u32_e32 v164, 0xc080, v0
	v_mov_b32_e32 v165, v1
	v_lshlrev_b64 v[164:165], 1, v[164:165]
	v_lshl_add_u64 v[168:169], s[42:43], 0, v[164:165]
	v_lshl_add_u64 v[164:165], s[40:41], 0, v[164:165]
	global_load_dwordx4 v[164:167], v[164:165], off
	global_load_dwordx4 v[168:171], v[168:169], off
	v_add_u32_e32 v172, 0x20000, v0
	v_mov_b32_e32 v173, v1
	v_lshlrev_b64 v[172:173], 1, v[172:173]
	v_lshl_add_u64 v[176:177], s[42:43], 0, v[172:173]
	v_lshl_add_u64 v[172:173], s[40:41], 0, v[172:173]
	global_load_dwordx4 v[172:175], v[172:173], off
	global_load_dwordx4 v[176:179], v[176:177], off
	v_add_u32_e32 v180, 0x20080, v0
	v_mov_b32_e32 v181, v1
	v_lshlrev_b64 v[180:181], 1, v[180:181]
	v_lshl_add_u64 v[184:185], s[42:43], 0, v[180:181]
	v_lshl_add_u64 v[180:181], s[40:41], 0, v[180:181]
	global_load_dwordx4 v[180:183], v[180:181], off
	global_load_dwordx4 v[184:187], v[184:185], off
	v_add_u32_e32 v188, 0x24000, v0
	v_mov_b32_e32 v189, v1
	v_lshlrev_b64 v[188:189], 1, v[188:189]
	v_lshl_add_u64 v[192:193], s[42:43], 0, v[188:189]
	v_lshl_add_u64 v[188:189], s[40:41], 0, v[188:189]
	global_load_dwordx4 v[188:191], v[188:189], off
	global_load_dwordx4 v[192:195], v[192:193], off
	v_add_u32_e32 v196, 0x24080, v0
	v_mov_b32_e32 v197, v1
	v_lshlrev_b64 v[196:197], 1, v[196:197]
	v_lshl_add_u64 v[200:201], s[42:43], 0, v[196:197]
	v_lshl_add_u64 v[196:197], s[40:41], 0, v[196:197]
	global_load_dwordx4 v[196:199], v[196:197], off
	global_load_dwordx4 v[200:203], v[200:201], off
	v_add_u32_e32 v204, 0x28000, v0
	v_mov_b32_e32 v205, v1
	v_lshlrev_b64 v[204:205], 1, v[204:205]
	v_lshl_add_u64 v[208:209], s[42:43], 0, v[204:205]
	v_lshl_add_u64 v[204:205], s[40:41], 0, v[204:205]
	global_load_dwordx4 v[204:207], v[204:205], off
	global_load_dwordx4 v[208:211], v[208:209], off
	v_add_u32_e32 v212, 0x28080, v0
	v_mov_b32_e32 v213, v1
	v_lshlrev_b64 v[212:213], 1, v[212:213]
	v_lshl_add_u64 v[216:217], s[42:43], 0, v[212:213]
	v_lshl_add_u64 v[212:213], s[40:41], 0, v[212:213]
	global_load_dwordx4 v[212:215], v[212:213], off
	global_load_dwordx4 v[216:219], v[216:217], off
	v_add_u32_e32 v74, 0xc080, v0
	v_mov_b32_e32 v75, v1
	v_lshlrev_b64 v[78:79], 1, v[74:75]
	s_waitcnt vmcnt(12)
; __device__ __forceinline__ void st8(bf16_t* p, f32x4 a, f32x4 b) { u32x4 w; w.x = pk2(a[0], a[1]); w.y = pk2(a[2], a[3]); w.z = pk2(b[0], b[1]); w.w = pk2(b[2], b[3]); *(u32x4*)p = w; }
; __device__ __forceinline__ void ld8(const bf16_t* p, f32x4& a, f32x4& b) { const u32x4 w = *(const u32x4*)p; a[0] = bflo(w.x); a[1] = bfhi(w.x); a[2] = bflo(w.y); a[3] = bfhi(w.y); b[0] = bflo(w.z); b[1] = bfhi(w.z); b[2] = bflo(w.w); b[3] = bfhi(w.w); }
;     __device__ __forceinline__ void operator()(ACC_T, const pg8::Unit& u, int wr, int wc, int fr, int fq) const {
;         const int row0 = u.pm * 256 + wr * 64 + fr, col0 = u.pn * 256 + wc * 32 + 8 * fq;
; #pragma unroll
;         for (int ai = 0; ai < 2; ++ai)
; #pragma unroll
;             for (int m = 0; m < 4; ++m) { const int row = row0 + ai * 128 + m * 16;
; #pragma unroll
;                 for (int bj = 0; bj < 2; ++bj) { const unsigned off = (unsigned)row * 1024u + col0 + bj * 128; f32x4 g0, g1; ld8(G + off, g0, g1);
;                     f32x4 v0 = acc[ai][bj][m][0] * g0, v1 = acc[ai][bj][m][1] * g1;
;                     if (MODE == 1) { f32x4 p0, p1; ld8(P + off, p0, p1); v0 += p0; v1 += p1; }
;                     st8(O + off, v0, v1); }
;                 asm volatile("" ::: "memory"); }
;     }
	v_lshlrev_b32_e32 v80, 16, v164
	v_and_b32_e32 v81, 0xffff0000, v164
	v_lshlrev_b32_e32 v82, 16, v165
	v_and_b32_e32 v83, 0xffff0000, v165
	v_lshlrev_b32_e32 v84, 16, v166
	v_and_b32_e32 v85, 0xffff0000, v166
	v_lshlrev_b32_e32 v86, 16, v167
	v_and_b32_e32 v87, 0xffff0000, v167
	v_lshlrev_b32_e32 v88, 16, v168
	v_and_b32_e32 v89, 0xffff0000, v168
	v_lshlrev_b32_e32 v74, 16, v169
	v_and_b32_e32 v75, 0xffff0000, v169
	v_lshlrev_b32_e32 v90, 16, v170
	v_and_b32_e32 v91, 0xffff0000, v170
	v_lshlrev_b32_e32 v76, 16, v171
	v_and_b32_e32 v77, 0xffff0000, v171
	v_pk_fma_f32 v[72:73], v[72:73], v[82:83], v[74:75]
	v_pk_fma_f32 v[70:71], v[70:71], v[80:81], v[88:89]
	v_pk_fma_f32 v[74:75], v[68:69], v[86:87], v[76:77]
	v_pk_fma_f32 v[68:69], v[66:67], v[84:85], v[90:91]
	v_lshl_add_u64 v[76:77], s[6:7], 0, v[78:79]
	v_cvt_pk_bf16_f32 v66, v70, v71
	v_cvt_pk_bf16_f32 v67, v72, v73
	v_cvt_pk_bf16_f32 v68, v68, v69
	v_cvt_pk_bf16_f32 v69, v74, v75
	global_store_dwordx4 v[76:77], v[66:69], off sc1
	s_nop 1
	v_add_u32_e32 v66, 0x20000, v0
	v_mov_b32_e32 v67, v1
	v_lshlrev_b64 v[70:71], 1, v[66:67]
	s_waitcnt vmcnt(11)
	v_lshlrev_b32_e32 v72, 16, v172
	v_and_b32_e32 v73, 0xffff0000, v172
	v_lshlrev_b32_e32 v74, 16, v173
	v_and_b32_e32 v75, 0xffff0000, v173
	v_lshlrev_b32_e32 v76, 16, v174
	v_and_b32_e32 v77, 0xffff0000, v174
	v_lshlrev_b32_e32 v78, 16, v175
	v_and_b32_e32 v79, 0xffff0000, v175
	v_lshlrev_b32_e32 v80, 16, v176
	v_and_b32_e32 v81, 0xffff0000, v176
	v_lshlrev_b32_e32 v66, 16, v177
	v_and_b32_e32 v67, 0xffff0000, v177
	v_lshlrev_b32_e32 v82, 16, v178
	v_and_b32_e32 v83, 0xffff0000, v178
	v_lshlrev_b32_e32 v68, 16, v179
	v_and_b32_e32 v69, 0xffff0000, v179
	v_pk_fma_f32 v[64:65], v[64:65], v[74:75], v[66:67]
	v_pk_fma_f32 v[62:63], v[62:63], v[72:73], v[80:81]
	v_pk_fma_f32 v[66:67], v[60:61], v[78:79], v[68:69]
	v_pk_fma_f32 v[60:61], v[58:59], v[76:77], v[82:83]
	v_lshl_add_u64 v[68:69], s[6:7], 0, v[70:71]
	v_cvt_pk_bf16_f32 v58, v62, v63
	v_cvt_pk_bf16_f32 v59, v64, v65
	v_cvt_pk_bf16_f32 v60, v60, v61
	v_cvt_pk_bf16_f32 v61, v66, v67
	global_store_dwordx4 v[68:69], v[58:61], off sc1
	s_nop 1
	v_add_u32_e32 v58, 0x20080, v0
	v_mov_b32_e32 v59, v1
	v_lshlrev_b64 v[62:63], 1, v[58:59]
	s_waitcnt vmcnt(10)
	v_lshlrev_b32_e32 v64, 16, v180
	v_and_b32_e32 v65, 0xffff0000, v180
	v_lshlrev_b32_e32 v66, 16, v181
	v_and_b32_e32 v67, 0xffff0000, v181
	v_lshlrev_b32_e32 v68, 16, v182
	v_and_b32_e32 v69, 0xffff0000, v182
	v_lshlrev_b32_e32 v70, 16, v183
	v_and_b32_e32 v71, 0xffff0000, v183
	v_lshlrev_b32_e32 v72, 16, v184
	v_and_b32_e32 v73, 0xffff0000, v184
	v_lshlrev_b32_e32 v58, 16, v185
	v_and_b32_e32 v59, 0xffff0000, v185
	v_lshlrev_b32_e32 v74, 16, v186
	v_and_b32_e32 v75, 0xffff0000, v186
	v_lshlrev_b32_e32 v60, 16, v187
	v_and_b32_e32 v61, 0xffff0000, v187
	v_pk_fma_f32 v[56:57], v[56:57], v[66:67], v[58:59]
	v_pk_fma_f32 v[54:55], v[54:55], v[64:65], v[72:73]
	v_pk_fma_f32 v[58:59], v[52:53], v[70:71], v[60:61]
	v_pk_fma_f32 v[52:53], v[50:51], v[68:69], v[74:75]
	v_lshl_add_u64 v[60:61], s[6:7], 0, v[62:63]
	v_cvt_pk_bf16_f32 v50, v54, v55
	v_cvt_pk_bf16_f32 v51, v56, v57
	v_cvt_pk_bf16_f32 v52, v52, v53
	v_cvt_pk_bf16_f32 v53, v58, v59
	global_store_dwordx4 v[60:61], v[50:53], off sc1
	s_nop 1
	v_add_u32_e32 v50, 0x24000, v0
	v_mov_b32_e32 v51, v1
	v_lshlrev_b64 v[54:55], 1, v[50:51]
	s_waitcnt vmcnt(9)
	v_lshlrev_b32_e32 v56, 16, v188
	v_and_b32_e32 v57, 0xffff0000, v188
	v_lshlrev_b32_e32 v58, 16, v189
	v_and_b32_e32 v59, 0xffff0000, v189
	v_lshlrev_b32_e32 v60, 16, v190
	v_and_b32_e32 v61, 0xffff0000, v190
	v_lshlrev_b32_e32 v62, 16, v191
	v_and_b32_e32 v63, 0xffff0000, v191
	v_lshlrev_b32_e32 v64, 16, v192
	v_and_b32_e32 v65, 0xffff0000, v192
	v_lshlrev_b32_e32 v50, 16, v193
	v_and_b32_e32 v51, 0xffff0000, v193
	v_lshlrev_b32_e32 v66, 16, v194
	v_and_b32_e32 v67, 0xffff0000, v194
	v_lshlrev_b32_e32 v52, 16, v195
	v_and_b32_e32 v53, 0xffff0000, v195
	v_pk_fma_f32 v[48:49], v[48:49], v[58:59], v[50:51]
	v_pk_fma_f32 v[46:47], v[46:47], v[56:57], v[64:65]
	v_pk_fma_f32 v[50:51], v[44:45], v[62:63], v[52:53]
	v_pk_fma_f32 v[44:45], v[42:43], v[60:61], v[66:67]
	v_lshl_add_u64 v[52:53], s[6:7], 0, v[54:55]
	v_cvt_pk_bf16_f32 v42, v46, v47
	v_cvt_pk_bf16_f32 v43, v48, v49
	v_cvt_pk_bf16_f32 v44, v44, v45
	v_cvt_pk_bf16_f32 v45, v50, v51
	global_store_dwordx4 v[52:53], v[42:45], off sc1
	s_nop 1
	v_add_u32_e32 v42, 0x24080, v0
	v_mov_b32_e32 v43, v1
	v_lshlrev_b64 v[46:47], 1, v[42:43]
	s_waitcnt vmcnt(8)
	v_lshlrev_b32_e32 v48, 16, v196
	v_and_b32_e32 v49, 0xffff0000, v196
	v_lshlrev_b32_e32 v50, 16, v197
	v_and_b32_e32 v51, 0xffff0000, v197
	v_lshlrev_b32_e32 v52, 16, v198
	v_and_b32_e32 v53, 0xffff0000, v198
	v_lshlrev_b32_e32 v54, 16, v199
	v_and_b32_e32 v55, 0xffff0000, v199
	v_lshlrev_b32_e32 v56, 16, v200
	v_and_b32_e32 v57, 0xffff0000, v200
	v_lshlrev_b32_e32 v42, 16, v201
	v_and_b32_e32 v43, 0xffff0000, v201
	v_lshlrev_b32_e32 v58, 16, v202
	v_and_b32_e32 v59, 0xffff0000, v202
	v_lshlrev_b32_e32 v44, 16, v203
	v_and_b32_e32 v45, 0xffff0000, v203
	v_pk_fma_f32 v[40:41], v[40:41], v[50:51], v[42:43]
	v_pk_fma_f32 v[38:39], v[38:39], v[48:49], v[56:57]
	v_pk_fma_f32 v[42:43], v[36:37], v[54:55], v[44:45]
	v_pk_fma_f32 v[36:37], v[34:35], v[52:53], v[58:59]
	v_lshl_add_u64 v[44:45], s[6:7], 0, v[46:47]
	v_cvt_pk_bf16_f32 v34, v38, v39
	v_cvt_pk_bf16_f32 v35, v40, v41
	v_cvt_pk_bf16_f32 v36, v36, v37
	v_cvt_pk_bf16_f32 v37, v42, v43
	global_store_dwordx4 v[44:45], v[34:37], off sc1
	s_nop 1
	v_add_u32_e32 v34, 0x28000, v0
	v_mov_b32_e32 v35, v1
	v_lshlrev_b64 v[38:39], 1, v[34:35]
	s_waitcnt vmcnt(7)
; #define PG8_BAR __builtin_amdgcn_s_barrier()
; #define PG8_SCHED __builtin_amdgcn_sched_barrier(0)
; __device__ __forceinline__ void st8(bf16_t* p, f32x4 a, f32x4 b) { u32x4 w; w.x = pk2(a[0], a[1]); w.y = pk2(a[2], a[3]); w.z = pk2(b[0], b[1]); w.w = pk2(b[2], b[3]); *(u32x4*)p = w; }
; __device__ __forceinline__ void ld8(const bf16_t* p, f32x4& a, f32x4& b) { const u32x4 w = *(const u32x4*)p; a[0] = bflo(w.x); a[1] = bfhi(w.x); a[2] = bflo(w.y); a[3] = bfhi(w.y); b[0] = bflo(w.z); b[1] = bfhi(w.z); b[2] = bflo(w.w); b[3] = bfhi(w.w); }
; template <class Epi, class Sched, bool ALIGN_EPI = false, bool SP2 = false>
; __device__ __forceinline__ void gemm_phase(PG8_LAS unsigned char* lds, const Gemm g, const Sched& S, const Epi& E) {
;     ...
;         if constexpr (ALIGN_EPI) { if (wr == 0) PG8_BAR; }
;         if constexpr (!Epi::AFTER_DRAIN) { PG8_SCHED; int fr_l = fr, fq_l = fq; asm volatile("" : "+v"(fr_l), "+v"(fq_l) :: "memory"); E(acc, cur, wr, wc, fr_l, fq_l); asm volatile("" ::: "memory"); PG8_SCHED; S.done(cur); }
;         if (!has_next) break;
; #pragma unroll
;         for (int a = 0; a < 2; ++a)
; #pragma unroll
;             for (int b = 0; b < 2; ++b)
; #pragma unroll
;                 for (int m = 0; m < 4; ++m)
; #pragma unroll
;                     for (int n = 0; n < 2; ++n) acc[a][b][m][n] = (f32x4){0.f, 0.f, 0.f, 0.f};
;         cur = nxt; cA = nA; cB = nB; ++ui;
;         if constexpr (ALIGN_EPI) { if (wr == 1) PG8_BAR; }
;     }
;     __device__ __forceinline__ void operator()(ACC_T, const pg8::Unit& u, int wr, int wc, int fr, int fq) const {
;         const int row0 = u.pm * 256 + wr * 64 + fr, col0 = u.pn * 256 + wc * 32 + 8 * fq;
; #pragma unroll
;         for (int ai = 0; ai < 2; ++ai)
; #pragma unroll
;             for (int m = 0; m < 4; ++m) { const int row = row0 + ai * 128 + m * 16;
; #pragma unroll
;                 for (int bj = 0; bj < 2; ++bj) { const unsigned off = (unsigned)row * 1024u + col0 + bj * 128; f32x4 g0, g1; ld8(G + off, g0, g1);
;                     f32x4 v0 = acc[ai][bj][m][0] * g0, v1 = acc[ai][bj][m][1] * g1;
;                     if (MODE == 1) { f32x4 p0, p1; ld8(P + off, p0, p1); v0 += p0; v1 += p1; }
;                     st8(O + off, v0, v1); }
;                 asm volatile("" ::: "memory"); }
;     }
	v_lshlrev_b32_e32 v40, 16, v204
	v_and_b32_e32 v41, 0xffff0000, v204
	v_lshlrev_b32_e32 v42, 16, v205
	v_and_b32_e32 v43, 0xffff0000, v205
	v_lshlrev_b32_e32 v44, 16, v206
	v_and_b32_e32 v45, 0xffff0000, v206
	v_lshlrev_b32_e32 v46, 16, v207
	v_and_b32_e32 v47, 0xffff0000, v207
	v_lshlrev_b32_e32 v48, 16, v208
	v_and_b32_e32 v49, 0xffff0000, v208
	v_lshlrev_b32_e32 v34, 16, v209
	v_and_b32_e32 v35, 0xffff0000, v209
	v_lshlrev_b32_e32 v50, 16, v210
	v_and_b32_e32 v51, 0xffff0000, v210
	v_lshlrev_b32_e32 v36, 16, v211
	v_and_b32_e32 v37, 0xffff0000, v211
	v_pk_fma_f32 v[32:33], v[32:33], v[42:43], v[34:35]
	v_pk_fma_f32 v[30:31], v[30:31], v[40:41], v[48:49]
	v_pk_fma_f32 v[34:35], v[28:29], v[46:47], v[36:37]
	v_pk_fma_f32 v[28:29], v[26:27], v[44:45], v[50:51]
	v_lshl_add_u64 v[36:37], s[6:7], 0, v[38:39]
	v_cvt_pk_bf16_f32 v26, v30, v31
	v_cvt_pk_bf16_f32 v27, v32, v33
	v_cvt_pk_bf16_f32 v28, v28, v29
	v_cvt_pk_bf16_f32 v29, v34, v35
	global_store_dwordx4 v[36:37], v[26:29], off sc1
	s_nop 1
	v_add_u32_e32 v26, 0x28080, v0
	v_mov_b32_e32 v27, v1
	v_lshlrev_b64 v[30:31], 1, v[26:27]
	s_waitcnt vmcnt(6)
	v_lshlrev_b32_e32 v32, 16, v212
	v_and_b32_e32 v33, 0xffff0000, v212
	v_lshlrev_b32_e32 v34, 16, v213
	v_and_b32_e32 v35, 0xffff0000, v213
	v_lshlrev_b32_e32 v36, 16, v214
	v_and_b32_e32 v37, 0xffff0000, v214
	v_lshlrev_b32_e32 v38, 16, v215
	v_and_b32_e32 v39, 0xffff0000, v215
	v_lshlrev_b32_e32 v40, 16, v216
	v_and_b32_e32 v41, 0xffff0000, v216
	v_lshlrev_b32_e32 v26, 16, v217
	v_and_b32_e32 v27, 0xffff0000, v217
	v_lshlrev_b32_e32 v42, 16, v218
	v_and_b32_e32 v43, 0xffff0000, v218
	v_lshlrev_b32_e32 v28, 16, v219
	v_and_b32_e32 v29, 0xffff0000, v219
	v_pk_fma_f32 v[24:25], v[24:25], v[34:35], v[26:27]
	v_pk_fma_f32 v[22:23], v[22:23], v[32:33], v[40:41]
	v_pk_fma_f32 v[26:27], v[20:21], v[38:39], v[28:29]
	v_pk_fma_f32 v[20:21], v[18:19], v[36:37], v[42:43]
	v_lshl_add_u64 v[28:29], s[6:7], 0, v[30:31]
	v_cvt_pk_bf16_f32 v18, v22, v23
	v_cvt_pk_bf16_f32 v19, v24, v25
	v_cvt_pk_bf16_f32 v20, v20, v21
	v_cvt_pk_bf16_f32 v21, v26, v27
	global_store_dwordx4 v[28:29], v[18:21], off sc1
	s_nop 1
	v_add_u32_e32 v18, 0x2c000, v0
	v_mov_b32_e32 v19, v1
	v_lshlrev_b64 v[22:23], 1, v[18:19]
	v_lshl_add_u64 v[18:19], s[40:41], 0, v[22:23]
	global_load_dwordx4 v[18:21], v[18:19], off
	v_add_u32_e32 v0, 0x2c080, v0
	s_waitcnt vmcnt(0)
	v_lshlrev_b32_e32 v24, 16, v18
	v_and_b32_e32 v25, 0xffff0000, v18
	v_lshlrev_b32_e32 v26, 16, v19
	v_and_b32_e32 v27, 0xffff0000, v19
	v_lshl_add_u64 v[18:19], s[42:43], 0, v[22:23]
	v_lshlrev_b32_e32 v28, 16, v20
	v_and_b32_e32 v29, 0xffff0000, v20
	v_lshlrev_b32_e32 v30, 16, v21
	v_and_b32_e32 v31, 0xffff0000, v21
	global_load_dwordx4 v[18:21], v[18:19], off
	s_waitcnt vmcnt(0)
	v_lshlrev_b32_e32 v32, 16, v18
	v_and_b32_e32 v33, 0xffff0000, v18
	v_lshlrev_b32_e32 v18, 16, v19
	v_and_b32_e32 v19, 0xffff0000, v19
	v_lshlrev_b32_e32 v34, 16, v20
	v_and_b32_e32 v35, 0xffff0000, v20
	v_lshlrev_b32_e32 v20, 16, v21
	v_and_b32_e32 v21, 0xffff0000, v21
	v_pk_fma_f32 v[16:17], v[16:17], v[26:27], v[18:19]
	v_pk_fma_f32 v[14:15], v[14:15], v[24:25], v[32:33]
	v_pk_fma_f32 v[18:19], v[12:13], v[30:31], v[20:21]
	v_pk_fma_f32 v[12:13], v[10:11], v[28:29], v[34:35]
	v_lshl_add_u64 v[20:21], s[6:7], 0, v[22:23]
	v_cvt_pk_bf16_f32 v10, v14, v15
	v_cvt_pk_bf16_f32 v11, v16, v17
	v_cvt_pk_bf16_f32 v12, v12, v13
	v_cvt_pk_bf16_f32 v13, v18, v19
	v_lshlrev_b64 v[14:15], 1, v[0:1]
	global_store_dwordx4 v[20:21], v[10:13], off sc1
	s_nop 1
	v_lshl_add_u64 v[10:11], s[40:41], 0, v[14:15]
	global_load_dwordx4 v[10:13], v[10:11], off
	s_waitcnt vmcnt(0)
	v_lshlrev_b32_e32 v16, 16, v10
	v_and_b32_e32 v17, 0xffff0000, v10
	v_lshlrev_b32_e32 v18, 16, v11
	v_and_b32_e32 v19, 0xffff0000, v11
	v_lshl_add_u64 v[10:11], s[42:43], 0, v[14:15]
	v_lshlrev_b32_e32 v20, 16, v12
	v_and_b32_e32 v21, 0xffff0000, v12
	v_lshlrev_b32_e32 v22, 16, v13
	v_and_b32_e32 v23, 0xffff0000, v13
	global_load_dwordx4 v[10:13], v[10:11], off
	s_waitcnt vmcnt(0)
	v_lshlrev_b32_e32 v24, 16, v10
	v_and_b32_e32 v25, 0xffff0000, v10
	v_lshlrev_b32_e32 v10, 16, v11
	v_and_b32_e32 v11, 0xffff0000, v11
	v_lshlrev_b32_e32 v26, 16, v12
	v_and_b32_e32 v27, 0xffff0000, v12
	v_lshlrev_b32_e32 v12, 16, v13
	v_and_b32_e32 v13, 0xffff0000, v13
	v_pk_fma_f32 v[8:9], v[8:9], v[18:19], v[10:11]
	v_pk_fma_f32 v[6:7], v[6:7], v[16:17], v[24:25]
	v_pk_fma_f32 v[10:11], v[4:5], v[22:23], v[12:13]
	v_pk_fma_f32 v[4:5], v[2:3], v[20:21], v[26:27]
	v_lshl_add_u64 v[12:13], s[6:7], 0, v[14:15]
	v_cvt_pk_bf16_f32 v2, v6, v7
	v_cvt_pk_bf16_f32 v3, v8, v9
	v_cvt_pk_bf16_f32 v4, v4, v5
	v_cvt_pk_bf16_f32 v5, v10, v11
	global_store_dwordx4 v[12:13], v[2:5], off sc1
	s_andn2_b64 vcc, exec, s[38:39]
	s_mov_b64 s[8:9], -1
	s_cbranch_vccnz .LBB0_1054
	s_andn2_b64 vcc, exec, s[4:5]
	s_cbranch_vccnz .LBB0_1053
	s_barrier
	s_branch .LBB0_1053
